# attention epilogues: gate rows also loaded as paired 16-byte pieces; output tile staged through a wave-private LDS image (xor-swizzled) so 8 lanes store one whole 128-byte row segment, written through
# speedup vs baseline: 1.1580x; 1.0124x over previous
.LBB0_128:
	v_exp_f32_e32 v0, v66
	v_exp_f32_e32 v67, v67
	v_exp_f32_e32 v68, v68
	v_exp_f32_e32 v69, v69
	v_add_f32_e32 v66, 0, v0
	v_exp_f32_e32 v70, v70
	v_add_f32_e32 v66, v67, v66
	v_exp_f32_e32 v71, v71
	v_add_f32_e32 v66, v68, v66
	v_exp_f32_e32 v72, v72
	v_add_f32_e32 v66, v69, v66
	v_exp_f32_e32 v98, v73
	v_add_f32_e32 v66, v70, v66
	v_exp_f32_e32 v74, v74
	v_add_f32_e32 v66, v71, v66
	v_exp_f32_e32 v75, v75
	v_add_f32_e32 v66, v72, v66
	v_exp_f32_e32 v76, v76
	v_add_f32_e32 v66, v98, v66
	v_exp_f32_e32 v77, v77
	v_add_f32_e32 v66, v74, v66
	v_exp_f32_e32 v78, v78
	v_add_f32_e32 v66, v75, v66
	v_exp_f32_e32 v79, v79
	v_add_f32_e32 v66, v76, v66
	v_exp_f32_e32 v80, v80
	v_add_f32_e32 v66, v77, v66
	v_exp_f32_e32 v81, v81
	v_add_f32_e32 v66, v78, v66
	v_add_f32_e32 v66, v79, v66
	v_add_f32_e32 v66, v80, v66
	v_add_f32_e32 v66, v81, v66
	v_add_f32_e32 v73, v166, v66
	v_cvt_pk_bf16_f32 v66, v0, v67
	v_cvt_pk_bf16_f32 v67, v68, v69
	v_cvt_pk_bf16_f32 v68, v70, v71
	v_cvt_pk_bf16_f32 v69, v72, v98
	s_waitcnt vmcnt(0)
	s_barrier
	v_mbcnt_lo_u32_b32 v116, -1, 0
	v_mbcnt_hi_u32_b32 v116, -1, v116
	v_mov_b32_e32 v148, s77
	v_lshlrev_b32_e32 v148, 6, v148
	v_and_b32_e32 v117, 31, v116
	v_lshrrev_b32_e32 v149, 5, v116
	v_lshl_add_u32 v122, v117, 7, v148
	v_and_b32_e32 v117, 7, v117
	v_sub_u32_e32 v118, 1, v149
	v_xor_b32_e32 v118, v118, v117
	v_lshl_add_u32 v118, v118, 4, v122
	v_sub_u32_e32 v119, 3, v149
	v_xor_b32_e32 v119, v119, v117
	v_lshl_add_u32 v119, v119, 4, v122
	v_sub_u32_e32 v120, 5, v149
	v_xor_b32_e32 v120, v120, v117
	v_lshl_add_u32 v120, v120, 4, v122
	v_sub_u32_e32 v121, 7, v149
	v_xor_b32_e32 v121, v121, v117
	v_lshl_add_u32 v121, v121, 4, v122
	v_lshrrev_b32_e32 v117, 3, v116
	v_and_b32_e32 v149, 7, v116
	v_lshl_add_u32 v122, v117, 7, v148
	v_xor_b32_e32 v148, v149, v117
	v_lshl_add_u32 v122, v148, 4, v122
	v_mul_u32_u24_e32 v144, 0x880, v117
	v_lshl_add_u32 v144, v149, 4, v144
	v_add_u32_e32 v145, 0x4400, v144
	v_add_u32_e32 v146, 0x8800, v144
	v_add_u32_e32 v147, 0xcc00, v144
	v_mbcnt_lo_u32_b32 v108, -1, 0
	v_mbcnt_hi_u32_b32 v108, -1, v108
	v_cmp_gt_u32_e32 vcc, 32, v108
	s_nop 1
	v_cndmask_b32_e64 v109, -1, 0, vcc
	v_cndmask_b32_e64 v108, -8, 16, vcc
	v_mfma_f32_32x32x16_bf16 v[18:33], v[82:85], v[66:69], v[18:33]
	v_mbcnt_lo_u32_b32 v0, -1, 0
	v_mbcnt_hi_u32_b32 v0, -1, v0
	s_movk_i32 s0, 0x100
	s_movk_i32 s5, 0xf3c0
	s_mov_b64 s[18:19], 0x44012c0
	s_mov_b32 s8, 0x4401000
	v_mfma_f32_32x32x16_bf16 v[2:17], v[86:89], v[66:69], v[2:17]
	v_cvt_pk_bf16_f32 v66, v74, v75
	v_cvt_pk_bf16_f32 v67, v76, v77
	v_cvt_pk_bf16_f32 v68, v78, v79
	v_cvt_pk_bf16_f32 v69, v80, v81
	s_nop 1
	v_mfma_f32_32x32x16_bf16 v[18:33], v[90:93], v[66:69], v[18:33]
	v_mfma_f32_32x32x16_bf16 v[2:17], v[94:97], v[66:69], v[2:17]
	v_add_u32_e32 v66, s77, v0
	v_cmp_gt_u32_e32 vcc, s0, v66
	v_mov_b32_e32 v68, s30
	v_mov_b32_e32 v69, s28
	v_cndmask_b32_e32 v68, v68, v69, vcc
	v_and_b32_e32 v66, 0xc0, v66
	v_and_b32_e32 v67, 31, v0
	v_lshl_or_b32 v66, v68, 8, v66
	v_or3_b32 v86, v66, v67, s40
	v_mov_b32_e32 v66, v142
	s_nop 1
	v_permlane32_swap_b32_e32 v142, v66
	v_add_f32_e32 v72, v142, v66
	v_mov_b64_e32 v[66:67], s[74:75]
	v_mad_u64_u32 v[66:67], s[0:1], v86, s4, v[66:67]
	v_mov_b32_e32 v68, 0x14c0
	v_mad_i32_i24 v67, s41, v68, v67
	s_lshl_b32 s28, s31, 1
	v_lshrrev_b32_e32 v0, 2, v0
	v_lshl_add_u64 v[68:69], v[66:67], 0, s[28:29]
	v_and_b32_e32 v0, 8, v0
	v_lshl_add_u64 v[68:69], v[68:69], 0, v[0:1]
	v_mad_u64_u32 v[88:89], s[0:1], v86, s5, v[66:67]
	v_mov_b32_e32 v94, 0xfffff3c0
	v_lshl_add_u64 v[90:91], v[68:69], 0, s[18:19]
	v_add_co_u32_e32 v68, vcc, s8, v68
	v_mad_i32_i24 v70, s41, v94, v89
	s_nop 0
	v_addc_co_u32_e32 v69, vcc, 0, v69, vcc
	v_sub_u32_e32 v89, v70, v86
	v_lshl_add_u64 v[114:115], v[90:91], 0, v[108:109]
	global_load_dwordx4 v[170:173], v[114:115], off
	global_load_dwordx4 v[174:177], v[114:115], off offset:32
	global_load_dwordx4 v[178:181], v[114:115], off offset:64
	global_load_dwordx4 v[182:185], v[114:115], off offset:96
	v_rcp_f32_e32 v72, v72
	v_lshl_add_u64 v[88:89], v[88:89], 0, s[28:29]
	s_mov_b64 s[0:1], 0x29800
	v_pk_mul_f32 v[50:51], v[50:51], v[72:73] op_sel_hi:[1,0]
	v_pk_mul_f32 v[52:53], v[52:53], v[72:73] op_sel_hi:[1,0]
	v_pk_mul_f32 v[54:55], v[54:55], v[72:73] op_sel_hi:[1,0]
	v_pk_mul_f32 v[56:57], v[56:57], v[72:73] op_sel_hi:[1,0]
	v_pk_mul_f32 v[34:35], v[34:35], v[72:73] op_sel_hi:[1,0]
	v_pk_mul_f32 v[36:37], v[36:37], v[72:73] op_sel_hi:[1,0]
	v_pk_mul_f32 v[38:39], v[38:39], v[72:73] op_sel_hi:[1,0]
	v_pk_mul_f32 v[40:41], v[40:41], v[72:73] op_sel_hi:[1,0]
	s_waitcnt vmcnt(3)
	v_permlane32_swap_b32_e32 v170, v172
	v_permlane32_swap_b32_e32 v171, v173
	v_mov_b32_e32 v82, v170
	v_mov_b32_e32 v83, v171
	v_mov_b32_e32 v84, v172
	v_mov_b32_e32 v85, v173
	v_lshlrev_b32_e32 v90, 16, v84
	v_and_b32_e32 v91, 0xffff0000, v84
	v_mul_f32_e32 v84, 0xbfb8aa3b, v90
	v_exp_f32_e32 v84, v84
	s_nop 0
	v_add_f32_e32 v84, 1.0, v84
	v_rcp_f32_e32 v92, v84
	v_mul_f32_e32 v84, 0xbfb8aa3b, v91
	v_exp_f32_e32 v84, v84
	s_nop 0
	v_add_f32_e32 v84, 1.0, v84
	v_rcp_f32_e32 v93, v84
	v_lshlrev_b32_e32 v84, 16, v85
	v_mul_f32_e32 v87, 0xbfb8aa3b, v84
	v_exp_f32_e32 v87, v87
	v_pk_mul_f32 v[90:91], v[92:93], v[90:91]
	v_and_b32_e32 v85, 0xffff0000, v85
	v_pk_mul_f32 v[50:51], v[50:51], v[90:91]
	v_add_f32_e32 v87, 1.0, v87
	v_rcp_f32_e32 v90, v87
	v_mul_f32_e32 v87, 0xbfb8aa3b, v85
	v_exp_f32_e32 v87, v87
	s_nop 0
	v_add_f32_e32 v87, 1.0, v87
	v_rcp_f32_e32 v91, v87
	s_nop 0
	v_pk_mul_f32 v[84:85], v[90:91], v[84:85]
	s_nop 0
	v_pk_mul_f32 v[52:53], v[52:53], v[84:85]
	v_cvt_pk_bf16_f32 v84, v50, v51
	v_cvt_pk_bf16_f32 v85, v52, v53
	s_waitcnt vmcnt(3)
	v_lshlrev_b32_e32 v52, 16, v82
	v_and_b32_e32 v53, 0xffff0000, v82
	v_mul_f32_e32 v82, 0xbfb8aa3b, v52
	v_exp_f32_e32 v82, v82
	v_lshl_add_u64 v[50:51], v[88:89], 0, v[0:1]
	v_mov_b32_e32 v106, v84
	v_mov_b32_e32 v107, v85
	v_add_f32_e32 v82, 1.0, v82
	v_rcp_f32_e32 v84, v82
	v_mul_f32_e32 v82, 0xbfb8aa3b, v53
	v_exp_f32_e32 v82, v82
	s_nop 0
	v_add_f32_e32 v82, 1.0, v82
	v_rcp_f32_e32 v85, v82
	s_nop 0
	v_pk_mul_f32 v[52:53], v[84:85], v[52:53]
	s_nop 0
	v_pk_mul_f32 v[52:53], v[54:55], v[52:53]
	v_lshlrev_b32_e32 v54, 16, v83
	v_and_b32_e32 v55, 0xffff0000, v83
	v_mul_f32_e32 v82, 0xbfb8aa3b, v54
	v_mul_f32_e32 v83, 0xbfb8aa3b, v55
	v_exp_f32_e32 v82, v82
	v_exp_f32_e32 v83, v83
	v_cvt_pk_bf16_f32 v52, v52, v53
	v_add_f32_e32 v82, 1.0, v82
	v_add_f32_e32 v83, 1.0, v83
	v_rcp_f32_e32 v82, v82
	v_rcp_f32_e32 v83, v83
	s_nop 0
	v_pk_mul_f32 v[54:55], v[82:83], v[54:55]
	s_nop 0
	v_pk_mul_f32 v[54:55], v[56:57], v[54:55]
	v_pk_mul_f32 v[56:57], v[58:59], v[72:73] op_sel_hi:[1,0]
	v_cvt_pk_bf16_f32 v53, v54, v55
	v_readfirstlane_b32 s98, v50
	v_readfirstlane_b32 s99, v51
	v_mov_b32_e32 v104, v52
	v_mov_b32_e32 v105, v53
	s_nop 1
	v_permlane32_swap_b32_e32 v104, v106
	v_permlane32_swap_b32_e32 v105, v107
	ds_write_b128 v118, v[104:107]
	s_waitcnt vmcnt(2)
	v_permlane32_swap_b32_e32 v174, v176
	v_permlane32_swap_b32_e32 v175, v177
	v_mov_b32_e32 v78, v174
	v_mov_b32_e32 v79, v175
	v_mov_b32_e32 v80, v176
	v_mov_b32_e32 v81, v177
	v_lshlrev_b32_e32 v52, 16, v80
	v_and_b32_e32 v53, 0xffff0000, v80
	v_mul_f32_e32 v54, 0xbfb8aa3b, v52
	v_mul_f32_e32 v55, 0xbfb8aa3b, v53
	v_exp_f32_e32 v54, v54
	v_exp_f32_e32 v55, v55
	v_pk_mul_f32 v[58:59], v[60:61], v[72:73] op_sel_hi:[1,0]
	v_add_f32_e32 v54, 1.0, v54
	v_add_f32_e32 v55, 1.0, v55
	v_rcp_f32_e32 v54, v54
	v_rcp_f32_e32 v55, v55
	s_nop 0
	v_pk_mul_f32 v[52:53], v[54:55], v[52:53]
	v_lshlrev_b32_e32 v54, 16, v81
	v_and_b32_e32 v55, 0xffff0000, v81
	v_pk_mul_f32 v[52:53], v[56:57], v[52:53]
	v_mul_f32_e32 v56, 0xbfb8aa3b, v54
	v_mul_f32_e32 v57, 0xbfb8aa3b, v55
	v_exp_f32_e32 v56, v56
	v_exp_f32_e32 v57, v57
	v_cvt_pk_bf16_f32 v52, v52, v53
	v_add_f32_e32 v56, 1.0, v56
	v_add_f32_e32 v57, 1.0, v57
	v_rcp_f32_e32 v56, v56
	v_rcp_f32_e32 v57, v57
	s_nop 0
	v_pk_mul_f32 v[54:55], v[56:57], v[54:55]
	s_nop 0
	v_pk_mul_f32 v[54:55], v[58:59], v[54:55]
	v_pk_mul_f32 v[56:57], v[62:63], v[72:73] op_sel_hi:[1,0]
	v_cvt_pk_bf16_f32 v53, v54, v55
	v_mov_b32_e32 v106, v52
	v_mov_b32_e32 v107, v53
	s_waitcnt vmcnt(2)
	v_lshlrev_b32_e32 v52, 16, v78
	v_and_b32_e32 v53, 0xffff0000, v78
	v_mul_f32_e32 v54, 0xbfb8aa3b, v52
	v_mul_f32_e32 v55, 0xbfb8aa3b, v53
	v_exp_f32_e32 v54, v54
	v_exp_f32_e32 v55, v55
	v_pk_mul_f32 v[58:59], v[64:65], v[72:73] op_sel_hi:[1,0]
	v_add_f32_e32 v54, 1.0, v54
	v_add_f32_e32 v55, 1.0, v55
	v_rcp_f32_e32 v54, v54
	v_rcp_f32_e32 v55, v55
	s_nop 0
	v_pk_mul_f32 v[52:53], v[54:55], v[52:53]
	v_lshlrev_b32_e32 v54, 16, v79
	v_and_b32_e32 v55, 0xffff0000, v79
	v_pk_mul_f32 v[52:53], v[56:57], v[52:53]
	v_mul_f32_e32 v56, 0xbfb8aa3b, v54
	v_mul_f32_e32 v57, 0xbfb8aa3b, v55
	v_exp_f32_e32 v56, v56
	v_exp_f32_e32 v57, v57
	v_cvt_pk_bf16_f32 v52, v52, v53
	v_add_f32_e32 v56, 1.0, v56
	v_add_f32_e32 v57, 1.0, v57
	v_rcp_f32_e32 v56, v56
	v_rcp_f32_e32 v57, v57
	s_nop 0
	v_pk_mul_f32 v[54:55], v[56:57], v[54:55]
	s_nop 0
	v_pk_mul_f32 v[54:55], v[58:59], v[54:55]
	s_nop 0
	v_cvt_pk_bf16_f32 v53, v54, v55
	v_mov_b32_e32 v104, v52
	v_mov_b32_e32 v105, v53
	s_nop 1
	v_permlane32_swap_b32_e32 v104, v106
	v_permlane32_swap_b32_e32 v105, v107
	ds_write_b128 v119, v[104:107]
	s_waitcnt vmcnt(1)
	v_permlane32_swap_b32_e32 v178, v180
	v_permlane32_swap_b32_e32 v179, v181
	v_mov_b32_e32 v74, v178
	v_mov_b32_e32 v75, v179
	v_mov_b32_e32 v76, v180
	v_mov_b32_e32 v77, v181
	v_lshlrev_b32_e32 v52, 16, v76
	v_and_b32_e32 v53, 0xffff0000, v76
	v_mul_f32_e32 v54, 0xbfb8aa3b, v52
	v_mul_f32_e32 v55, 0xbfb8aa3b, v53
	v_exp_f32_e32 v54, v54
	v_exp_f32_e32 v55, v55
	v_add_f32_e32 v54, 1.0, v54
	v_add_f32_e32 v55, 1.0, v55
	v_rcp_f32_e32 v54, v54
	v_rcp_f32_e32 v55, v55
	s_nop 0
	v_pk_mul_f32 v[52:53], v[54:55], v[52:53]
	s_nop 0
	v_pk_mul_f32 v[34:35], v[34:35], v[52:53]
	v_lshlrev_b32_e32 v52, 16, v77
	v_and_b32_e32 v53, 0xffff0000, v77
	v_mul_f32_e32 v54, 0xbfb8aa3b, v52
	v_mul_f32_e32 v55, 0xbfb8aa3b, v53
	v_exp_f32_e32 v54, v54
	v_exp_f32_e32 v55, v55
	v_cvt_pk_bf16_f32 v34, v34, v35
	v_add_f32_e32 v54, 1.0, v54
	v_add_f32_e32 v55, 1.0, v55
	v_rcp_f32_e32 v54, v54
	v_rcp_f32_e32 v55, v55
	s_nop 0
	v_pk_mul_f32 v[52:53], v[54:55], v[52:53]
	s_nop 0
	v_pk_mul_f32 v[36:37], v[36:37], v[52:53]
	s_nop 0
	v_cvt_pk_bf16_f32 v35, v36, v37
	v_mov_b32_e32 v106, v34
	v_mov_b32_e32 v107, v35
	s_waitcnt vmcnt(1)
	v_lshlrev_b32_e32 v34, 16, v74
	v_and_b32_e32 v35, 0xffff0000, v74
	v_mul_f32_e32 v36, 0xbfb8aa3b, v34
	v_mul_f32_e32 v37, 0xbfb8aa3b, v35
	v_exp_f32_e32 v36, v36
	v_exp_f32_e32 v37, v37
	v_add_f32_e32 v36, 1.0, v36
	v_add_f32_e32 v37, 1.0, v37
	v_rcp_f32_e32 v36, v36
	v_rcp_f32_e32 v37, v37
	s_nop 0
	v_pk_mul_f32 v[34:35], v[36:37], v[34:35]
	v_lshlrev_b32_e32 v36, 16, v75
	v_and_b32_e32 v37, 0xffff0000, v75
	v_pk_mul_f32 v[34:35], v[38:39], v[34:35]
	v_mul_f32_e32 v38, 0xbfb8aa3b, v36
	v_mul_f32_e32 v39, 0xbfb8aa3b, v37
	v_exp_f32_e32 v38, v38
	v_exp_f32_e32 v39, v39
	v_cvt_pk_bf16_f32 v34, v34, v35
	v_add_f32_e32 v38, 1.0, v38
	v_add_f32_e32 v39, 1.0, v39
	v_rcp_f32_e32 v38, v38
	v_rcp_f32_e32 v39, v39
	s_nop 0
	v_pk_mul_f32 v[36:37], v[38:39], v[36:37]
	s_nop 0
	v_pk_mul_f32 v[36:37], v[40:41], v[36:37]
	v_pk_mul_f32 v[38:39], v[42:43], v[72:73] op_sel_hi:[1,0]
	v_cvt_pk_bf16_f32 v35, v36, v37
	v_mov_b32_e32 v104, v34
	v_mov_b32_e32 v105, v35
	s_nop 1
	v_permlane32_swap_b32_e32 v104, v106
	v_permlane32_swap_b32_e32 v105, v107
	ds_write_b128 v120, v[104:107]
	s_waitcnt vmcnt(0)
	v_permlane32_swap_b32_e32 v182, v184
	v_permlane32_swap_b32_e32 v183, v185
	v_mov_b32_e32 v68, v182
	v_mov_b32_e32 v69, v183
	v_mov_b32_e32 v70, v184
	v_mov_b32_e32 v71, v185
	v_lshlrev_b32_e32 v34, 16, v70
	v_and_b32_e32 v35, 0xffff0000, v70
	v_mul_f32_e32 v36, 0xbfb8aa3b, v34
	v_mul_f32_e32 v37, 0xbfb8aa3b, v35
	v_exp_f32_e32 v36, v36
	v_exp_f32_e32 v37, v37
	v_pk_mul_f32 v[40:41], v[44:45], v[72:73] op_sel_hi:[1,0]
	v_add_f32_e32 v36, 1.0, v36
	v_add_f32_e32 v37, 1.0, v37
	v_rcp_f32_e32 v36, v36
	v_rcp_f32_e32 v37, v37
	s_nop 0
	v_pk_mul_f32 v[34:35], v[36:37], v[34:35]
	v_lshlrev_b32_e32 v36, 16, v71
	v_and_b32_e32 v37, 0xffff0000, v71
	v_pk_mul_f32 v[34:35], v[38:39], v[34:35]
	v_mul_f32_e32 v38, 0xbfb8aa3b, v36
	v_mul_f32_e32 v39, 0xbfb8aa3b, v37
	v_exp_f32_e32 v38, v38
	v_exp_f32_e32 v39, v39
	v_cvt_pk_bf16_f32 v34, v34, v35
	v_add_f32_e32 v38, 1.0, v38
	v_add_f32_e32 v39, 1.0, v39
	v_rcp_f32_e32 v38, v38
	v_rcp_f32_e32 v39, v39
	s_nop 0
	v_pk_mul_f32 v[36:37], v[38:39], v[36:37]
	s_nop 0
	v_pk_mul_f32 v[36:37], v[40:41], v[36:37]
	v_pk_mul_f32 v[38:39], v[46:47], v[72:73] op_sel_hi:[1,0]
	v_cvt_pk_bf16_f32 v35, v36, v37
	v_mov_b32_e32 v106, v34
	v_mov_b32_e32 v107, v35
	s_waitcnt vmcnt(0)
	v_lshlrev_b32_e32 v34, 16, v68
	v_and_b32_e32 v35, 0xffff0000, v68
	v_mul_f32_e32 v36, 0xbfb8aa3b, v34
	v_mul_f32_e32 v37, 0xbfb8aa3b, v35
	v_exp_f32_e32 v36, v36
	v_exp_f32_e32 v37, v37
	v_pk_mul_f32 v[40:41], v[48:49], v[72:73] op_sel_hi:[1,0]
	v_add_f32_e32 v36, 1.0, v36
	v_add_f32_e32 v37, 1.0, v37
	v_rcp_f32_e32 v36, v36
	v_rcp_f32_e32 v37, v37
	s_nop 0
	v_pk_mul_f32 v[34:35], v[36:37], v[34:35]
	v_lshlrev_b32_e32 v36, 16, v69
	v_and_b32_e32 v37, 0xffff0000, v69
	v_pk_mul_f32 v[34:35], v[38:39], v[34:35]
	v_mul_f32_e32 v38, 0xbfb8aa3b, v36
	v_mul_f32_e32 v39, 0xbfb8aa3b, v37
	v_exp_f32_e32 v38, v38
	v_exp_f32_e32 v39, v39
	v_cvt_pk_bf16_f32 v34, v34, v35
	v_add_f32_e32 v38, 1.0, v38
	v_add_f32_e32 v39, 1.0, v39
	v_rcp_f32_e32 v38, v38
	v_rcp_f32_e32 v39, v39
	s_nop 0
	v_pk_mul_f32 v[36:37], v[38:39], v[36:37]
	s_nop 0
	v_pk_mul_f32 v[36:37], v[40:41], v[36:37]
	v_or_b32_e32 v38, 32, v86
	v_cvt_pk_bf16_f32 v35, v36, v37
	v_mov_b32_e32 v104, v34
	v_mov_b32_e32 v105, v35
	s_nop 1
	v_permlane32_swap_b32_e32 v104, v106
	v_permlane32_swap_b32_e32 v105, v107
	ds_write_b128 v121, v[104:107]
	ds_read_b128 v[124:127], v122
	ds_read_b128 v[128:131], v122 offset:1024
	ds_read_b128 v[132:135], v122 offset:2048
	ds_read_b128 v[136:139], v122 offset:3072
	s_waitcnt lgkmcnt(3)
	global_store_dwordx4 v144, v[124:127], s[98:99] offset:1536 sc0 sc1
	s_waitcnt lgkmcnt(2)
	global_store_dwordx4 v145, v[128:131], s[98:99] offset:1536 sc0 sc1
	s_waitcnt lgkmcnt(1)
	global_store_dwordx4 v146, v[132:135], s[98:99] offset:1536 sc0 sc1
	s_waitcnt lgkmcnt(0)
	global_store_dwordx4 v147, v[136:139], s[98:99] offset:1536 sc0 sc1
	v_mov_b32_e32 v34, v73
	s_nop 1
	v_permlane32_swap_b32_e32 v73, v34
	v_add_f32_e32 v54, v73, v34
	v_lshl_add_u64 v[34:35], v[66:67], 0, s[0:1]
	v_lshl_add_u64 v[36:37], v[34:35], 0, s[28:29]
	v_mad_u64_u32 v[52:53], s[0:1], v38, s5, v[34:35]
	v_mad_i32_i24 v34, s41, v94, v53
	v_lshl_add_u64 v[36:37], v[36:37], 0, v[0:1]
	v_sub_u32_e32 v53, v34, v38
	v_lshl_add_u64 v[34:35], v[36:37], 0, s[18:19]
	v_add_co_u32_e32 v36, vcc, s8, v36
	v_lshl_add_u64 v[52:53], v[52:53], 0, s[28:29]
	s_nop 0
	v_addc_co_u32_e32 v37, vcc, 0, v37, vcc
	v_lshl_add_u64 v[116:117], v[34:35], 0, v[108:109]
	global_load_dwordx4 v[186:189], v[116:117], off
	global_load_dwordx4 v[190:193], v[116:117], off offset:32
	global_load_dwordx4 v[194:197], v[116:117], off offset:64
	global_load_dwordx4 v[198:201], v[116:117], off offset:96
	v_rcp_f32_e32 v34, v54
	s_waitcnt vmcnt(3)
	v_permlane32_swap_b32_e32 v186, v188
	v_permlane32_swap_b32_e32 v187, v189
	v_mov_b32_e32 v48, v186
	v_mov_b32_e32 v49, v187
	v_mov_b32_e32 v50, v188
	v_mov_b32_e32 v51, v189
	v_lshlrev_b32_e32 v54, 16, v50
	v_mul_f32_e32 v35, 0xbfb8aa3b, v54
	v_exp_f32_e32 v35, v35
	v_and_b32_e32 v55, 0xffff0000, v50
	v_lshlrev_b32_e32 v50, 16, v51
	v_and_b32_e32 v51, 0xffff0000, v51
	v_add_f32_e32 v35, 1.0, v35
	v_rcp_f32_e32 v56, v35
	v_pk_mul_f32 v[18:19], v[18:19], v[34:35] op_sel_hi:[1,0]
	v_mul_f32_e32 v35, 0xbfb8aa3b, v55
	v_exp_f32_e32 v35, v35
	s_nop 0
	v_add_f32_e32 v35, 1.0, v35
	v_rcp_f32_e32 v57, v35
	v_mul_f32_e32 v35, 0xbfb8aa3b, v50
	v_exp_f32_e32 v35, v35
	v_pk_mul_f32 v[54:55], v[56:57], v[54:55]
	s_nop 0
	v_pk_mul_f32 v[18:19], v[18:19], v[54:55]
	v_add_f32_e32 v35, 1.0, v35
	v_rcp_f32_e32 v54, v35
	v_pk_mul_f32 v[20:21], v[20:21], v[34:35] op_sel_hi:[1,0]
	v_mul_f32_e32 v35, 0xbfb8aa3b, v51
	v_exp_f32_e32 v35, v35
	s_nop 0
	v_add_f32_e32 v35, 1.0, v35
	v_rcp_f32_e32 v55, v35
	v_pk_mul_f32 v[22:23], v[22:23], v[34:35] op_sel_hi:[1,0]
	v_pk_mul_f32 v[24:25], v[24:25], v[34:35] op_sel_hi:[1,0]
	v_pk_mul_f32 v[2:3], v[2:3], v[34:35] op_sel_hi:[1,0]
	v_pk_mul_f32 v[50:51], v[54:55], v[50:51]
	v_pk_mul_f32 v[4:5], v[4:5], v[34:35] op_sel_hi:[1,0]
	v_pk_mul_f32 v[20:21], v[20:21], v[50:51]
	v_cvt_pk_bf16_f32 v50, v18, v19
	v_cvt_pk_bf16_f32 v51, v20, v21
	s_waitcnt vmcnt(3)
	v_lshlrev_b32_e32 v20, 16, v48
	v_lshl_add_u64 v[18:19], v[52:53], 0, v[0:1]
	v_mul_f32_e32 v0, 0xbfb8aa3b, v20
	v_exp_f32_e32 v0, v0
	v_and_b32_e32 v21, 0xffff0000, v48
	v_mov_b32_e32 v106, v50
	v_mov_b32_e32 v107, v51
	v_pk_mul_f32 v[6:7], v[6:7], v[34:35] op_sel_hi:[1,0]
	v_add_f32_e32 v0, 1.0, v0
	v_rcp_f32_e32 v50, v0
	v_mul_f32_e32 v0, 0xbfb8aa3b, v21
	v_exp_f32_e32 v0, v0
	v_pk_mul_f32 v[8:9], v[8:9], v[34:35] op_sel_hi:[1,0]
	v_add_f32_e32 v0, 1.0, v0
	v_rcp_f32_e32 v51, v0
	s_nop 0
	v_pk_mul_f32 v[20:21], v[50:51], v[20:21]
	s_nop 0
	v_pk_mul_f32 v[20:21], v[22:23], v[20:21]
	v_lshlrev_b32_e32 v22, 16, v49
	v_mul_f32_e32 v0, 0xbfb8aa3b, v22
	v_exp_f32_e32 v0, v0
	v_and_b32_e32 v23, 0xffff0000, v49
	v_cvt_pk_bf16_f32 v20, v20, v21
	v_add_f32_e32 v0, 1.0, v0
	v_rcp_f32_e32 v48, v0
	v_mul_f32_e32 v0, 0xbfb8aa3b, v23
	v_exp_f32_e32 v0, v0
	s_nop 0
	v_add_f32_e32 v0, 1.0, v0
	v_rcp_f32_e32 v49, v0
	s_nop 0
	v_pk_mul_f32 v[22:23], v[48:49], v[22:23]
	s_nop 0
	v_pk_mul_f32 v[22:23], v[24:25], v[22:23]
	v_pk_mul_f32 v[24:25], v[26:27], v[34:35] op_sel_hi:[1,0]
	v_cvt_pk_bf16_f32 v21, v22, v23
	v_readfirstlane_b32 s98, v18
	v_readfirstlane_b32 s99, v19
	v_mov_b32_e32 v104, v20
	v_mov_b32_e32 v105, v21
	s_nop 1
	v_permlane32_swap_b32_e32 v104, v106
	v_permlane32_swap_b32_e32 v105, v107
	ds_write_b128 v118, v[104:107]
	s_waitcnt vmcnt(2)
	v_permlane32_swap_b32_e32 v190, v192
	v_permlane32_swap_b32_e32 v191, v193
	v_mov_b32_e32 v44, v190
	v_mov_b32_e32 v45, v191
	v_mov_b32_e32 v46, v192
	v_mov_b32_e32 v47, v193
	v_lshlrev_b32_e32 v20, 16, v46
	v_mul_f32_e32 v0, 0xbfb8aa3b, v20
	v_exp_f32_e32 v0, v0
	v_and_b32_e32 v21, 0xffff0000, v46
	v_pk_mul_f32 v[26:27], v[28:29], v[34:35] op_sel_hi:[1,0]
	v_add_f32_e32 v0, 1.0, v0
	v_rcp_f32_e32 v22, v0
	v_mul_f32_e32 v0, 0xbfb8aa3b, v21
	v_exp_f32_e32 v0, v0
	s_nop 0
	v_add_f32_e32 v0, 1.0, v0
	v_rcp_f32_e32 v23, v0
	s_nop 0
	v_pk_mul_f32 v[20:21], v[22:23], v[20:21]
	v_lshlrev_b32_e32 v22, 16, v47
	v_mul_f32_e32 v0, 0xbfb8aa3b, v22
	v_exp_f32_e32 v0, v0
	v_and_b32_e32 v23, 0xffff0000, v47
	v_pk_mul_f32 v[20:21], v[24:25], v[20:21]
	v_add_f32_e32 v0, 1.0, v0
	v_rcp_f32_e32 v24, v0
	v_mul_f32_e32 v0, 0xbfb8aa3b, v23
	v_exp_f32_e32 v0, v0
	v_cvt_pk_bf16_f32 v20, v20, v21
	v_add_f32_e32 v0, 1.0, v0
	v_rcp_f32_e32 v25, v0
	s_nop 0
	v_pk_mul_f32 v[22:23], v[24:25], v[22:23]
	s_nop 0
	v_pk_mul_f32 v[22:23], v[26:27], v[22:23]
	v_pk_mul_f32 v[24:25], v[30:31], v[34:35] op_sel_hi:[1,0]
	v_cvt_pk_bf16_f32 v21, v22, v23
	v_mov_b32_e32 v106, v20
	v_mov_b32_e32 v107, v21
	s_waitcnt vmcnt(2)
	v_lshlrev_b32_e32 v20, 16, v44
	v_mul_f32_e32 v0, 0xbfb8aa3b, v20
	v_exp_f32_e32 v0, v0
	v_and_b32_e32 v21, 0xffff0000, v44
	v_pk_mul_f32 v[26:27], v[32:33], v[34:35] op_sel_hi:[1,0]
	v_add_f32_e32 v0, 1.0, v0
	v_rcp_f32_e32 v22, v0
	v_mul_f32_e32 v0, 0xbfb8aa3b, v21
	v_exp_f32_e32 v0, v0
	s_nop 0
	v_add_f32_e32 v0, 1.0, v0
	v_rcp_f32_e32 v23, v0
	s_nop 0
	v_pk_mul_f32 v[20:21], v[22:23], v[20:21]
	v_lshlrev_b32_e32 v22, 16, v45
	v_mul_f32_e32 v0, 0xbfb8aa3b, v22
	v_exp_f32_e32 v0, v0
	v_and_b32_e32 v23, 0xffff0000, v45
	v_pk_mul_f32 v[20:21], v[24:25], v[20:21]
	v_add_f32_e32 v0, 1.0, v0
	v_rcp_f32_e32 v24, v0
	v_mul_f32_e32 v0, 0xbfb8aa3b, v23
	v_exp_f32_e32 v0, v0
	v_cvt_pk_bf16_f32 v20, v20, v21
	v_add_f32_e32 v0, 1.0, v0
	v_rcp_f32_e32 v25, v0
	s_nop 0
	v_pk_mul_f32 v[22:23], v[24:25], v[22:23]
	s_nop 0
	v_pk_mul_f32 v[22:23], v[26:27], v[22:23]
	s_nop 0
	v_cvt_pk_bf16_f32 v21, v22, v23
	v_mov_b32_e32 v104, v20
	v_mov_b32_e32 v105, v21
	s_nop 1
	v_permlane32_swap_b32_e32 v104, v106
	v_permlane32_swap_b32_e32 v105, v107
	ds_write_b128 v119, v[104:107]
	s_waitcnt vmcnt(1)
	v_permlane32_swap_b32_e32 v194, v196
	v_permlane32_swap_b32_e32 v195, v197
	v_mov_b32_e32 v40, v194
	v_mov_b32_e32 v41, v195
	v_mov_b32_e32 v42, v196
	v_mov_b32_e32 v43, v197
	v_lshlrev_b32_e32 v20, 16, v42
	v_mul_f32_e32 v0, 0xbfb8aa3b, v20
	v_exp_f32_e32 v0, v0
	v_and_b32_e32 v21, 0xffff0000, v42
	v_add_f32_e32 v0, 1.0, v0
	v_rcp_f32_e32 v22, v0
	v_mul_f32_e32 v0, 0xbfb8aa3b, v21
	v_exp_f32_e32 v0, v0
	s_nop 0
	v_add_f32_e32 v0, 1.0, v0
	v_rcp_f32_e32 v23, v0
	s_nop 0
	v_pk_mul_f32 v[20:21], v[22:23], v[20:21]
	s_nop 0
	v_pk_mul_f32 v[2:3], v[2:3], v[20:21]
	v_lshlrev_b32_e32 v20, 16, v43
	v_mul_f32_e32 v0, 0xbfb8aa3b, v20
	v_exp_f32_e32 v0, v0
	v_and_b32_e32 v21, 0xffff0000, v43
	v_cvt_pk_bf16_f32 v2, v2, v3
	v_add_f32_e32 v0, 1.0, v0
	v_rcp_f32_e32 v22, v0
	v_mul_f32_e32 v0, 0xbfb8aa3b, v21
	v_exp_f32_e32 v0, v0
	s_nop 0
	v_add_f32_e32 v0, 1.0, v0
	v_rcp_f32_e32 v23, v0
	s_nop 0
	v_pk_mul_f32 v[20:21], v[22:23], v[20:21]
	s_nop 0
	v_pk_mul_f32 v[4:5], v[4:5], v[20:21]
	s_nop 0
	v_cvt_pk_bf16_f32 v3, v4, v5
	v_mov_b32_e32 v106, v2
	v_mov_b32_e32 v107, v3
	s_waitcnt vmcnt(1)
	v_lshlrev_b32_e32 v2, 16, v40
	v_mul_f32_e32 v0, 0xbfb8aa3b, v2
	v_exp_f32_e32 v0, v0
	v_and_b32_e32 v3, 0xffff0000, v40
	v_add_f32_e32 v0, 1.0, v0
	v_rcp_f32_e32 v4, v0
	v_mul_f32_e32 v0, 0xbfb8aa3b, v3
	v_exp_f32_e32 v0, v0
	s_nop 0
	v_add_f32_e32 v0, 1.0, v0
	v_rcp_f32_e32 v5, v0
	s_nop 0
	v_pk_mul_f32 v[2:3], v[4:5], v[2:3]
	v_lshlrev_b32_e32 v4, 16, v41
	v_mul_f32_e32 v0, 0xbfb8aa3b, v4
	v_exp_f32_e32 v0, v0
	v_and_b32_e32 v5, 0xffff0000, v41
	v_pk_mul_f32 v[2:3], v[6:7], v[2:3]
	v_add_f32_e32 v0, 1.0, v0
	v_rcp_f32_e32 v6, v0
	v_mul_f32_e32 v0, 0xbfb8aa3b, v5
	v_exp_f32_e32 v0, v0
	v_cvt_pk_bf16_f32 v2, v2, v3
	v_add_f32_e32 v0, 1.0, v0
	v_rcp_f32_e32 v7, v0
	s_nop 0
	v_pk_mul_f32 v[4:5], v[6:7], v[4:5]
	s_nop 0
	v_pk_mul_f32 v[4:5], v[8:9], v[4:5]
	v_pk_mul_f32 v[6:7], v[10:11], v[34:35] op_sel_hi:[1,0]
	v_cvt_pk_bf16_f32 v3, v4, v5
	v_mov_b32_e32 v104, v2
	v_mov_b32_e32 v105, v3
	s_nop 1
	v_permlane32_swap_b32_e32 v104, v106
	v_permlane32_swap_b32_e32 v105, v107
	ds_write_b128 v120, v[104:107]
	s_waitcnt vmcnt(0)
	v_permlane32_swap_b32_e32 v198, v200
	v_permlane32_swap_b32_e32 v199, v201
	v_mov_b32_e32 v36, v198
	v_mov_b32_e32 v37, v199
	v_mov_b32_e32 v38, v200
	v_mov_b32_e32 v39, v201
	v_lshlrev_b32_e32 v2, 16, v38
	v_mul_f32_e32 v0, 0xbfb8aa3b, v2
	v_exp_f32_e32 v0, v0
	v_and_b32_e32 v3, 0xffff0000, v38
	v_pk_mul_f32 v[8:9], v[12:13], v[34:35] op_sel_hi:[1,0]
	v_add_f32_e32 v0, 1.0, v0
	v_rcp_f32_e32 v4, v0
	v_mul_f32_e32 v0, 0xbfb8aa3b, v3
	v_exp_f32_e32 v0, v0
	s_nop 0
	v_add_f32_e32 v0, 1.0, v0
	v_rcp_f32_e32 v5, v0
	s_nop 0
	v_pk_mul_f32 v[2:3], v[4:5], v[2:3]
	v_lshlrev_b32_e32 v4, 16, v39
	v_mul_f32_e32 v0, 0xbfb8aa3b, v4
	v_exp_f32_e32 v0, v0
	v_and_b32_e32 v5, 0xffff0000, v39
	v_pk_mul_f32 v[2:3], v[6:7], v[2:3]
	v_add_f32_e32 v0, 1.0, v0
	v_rcp_f32_e32 v6, v0
	v_mul_f32_e32 v0, 0xbfb8aa3b, v5
	v_exp_f32_e32 v0, v0
	v_cvt_pk_bf16_f32 v2, v2, v3
	v_add_f32_e32 v0, 1.0, v0
	v_rcp_f32_e32 v7, v0
	s_nop 0
	v_pk_mul_f32 v[4:5], v[6:7], v[4:5]
	s_nop 0
	v_pk_mul_f32 v[4:5], v[8:9], v[4:5]
	v_pk_mul_f32 v[6:7], v[14:15], v[34:35] op_sel_hi:[1,0]
	v_cvt_pk_bf16_f32 v3, v4, v5
	v_mov_b32_e32 v106, v2
	v_mov_b32_e32 v107, v3
	s_waitcnt vmcnt(0)
	v_lshlrev_b32_e32 v2, 16, v36
	v_mul_f32_e32 v0, 0xbfb8aa3b, v2
	v_exp_f32_e32 v0, v0
	v_and_b32_e32 v3, 0xffff0000, v36
	v_pk_mul_f32 v[8:9], v[16:17], v[34:35] op_sel_hi:[1,0]
	v_add_f32_e32 v0, 1.0, v0
	v_rcp_f32_e32 v4, v0
	v_mul_f32_e32 v0, 0xbfb8aa3b, v3
	v_exp_f32_e32 v0, v0
	s_nop 0
	v_add_f32_e32 v0, 1.0, v0
	v_rcp_f32_e32 v5, v0
	s_nop 0
	v_pk_mul_f32 v[2:3], v[4:5], v[2:3]
	v_lshlrev_b32_e32 v4, 16, v37
	v_mul_f32_e32 v0, 0xbfb8aa3b, v4
	v_exp_f32_e32 v0, v0
	v_and_b32_e32 v5, 0xffff0000, v37
	v_pk_mul_f32 v[2:3], v[6:7], v[2:3]
	v_add_f32_e32 v0, 1.0, v0
	v_rcp_f32_e32 v6, v0
	v_mul_f32_e32 v0, 0xbfb8aa3b, v5
	v_exp_f32_e32 v0, v0
	v_cvt_pk_bf16_f32 v2, v2, v3
	v_add_f32_e32 v0, 1.0, v0
	v_rcp_f32_e32 v7, v0
	s_nop 0
	v_pk_mul_f32 v[4:5], v[6:7], v[4:5]
	s_nop 0
	v_pk_mul_f32 v[4:5], v[8:9], v[4:5]
	s_nop 0
	v_cvt_pk_bf16_f32 v3, v4, v5
	v_mov_b32_e32 v104, v2
	v_mov_b32_e32 v105, v3
	s_nop 1
	v_permlane32_swap_b32_e32 v104, v106
	v_permlane32_swap_b32_e32 v105, v107
	ds_write_b128 v121, v[104:107]
	ds_read_b128 v[124:127], v122
	ds_read_b128 v[128:131], v122 offset:1024
	ds_read_b128 v[132:135], v122 offset:2048
	ds_read_b128 v[136:139], v122 offset:3072
	s_waitcnt lgkmcnt(3)
	global_store_dwordx4 v144, v[124:127], s[98:99] offset:1536 sc0 sc1
	s_waitcnt lgkmcnt(2)
	global_store_dwordx4 v145, v[128:131], s[98:99] offset:1536 sc0 sc1
	s_waitcnt lgkmcnt(1)
	global_store_dwordx4 v146, v[132:135], s[98:99] offset:1536 sc0 sc1
	s_waitcnt lgkmcnt(0)
	global_store_dwordx4 v147, v[136:139], s[98:99] offset:1536 sc0 sc1

.LBB0_175:
	s_waitcnt vmcnt(0) lgkmcnt(0)
	s_barrier
	v_mbcnt_lo_u32_b32 v116, -1, 0
	v_mbcnt_hi_u32_b32 v116, -1, v116
	v_mov_b32_e32 v148, s77
	v_lshlrev_b32_e32 v148, 6, v148
	v_and_b32_e32 v117, 31, v116
	v_lshrrev_b32_e32 v149, 5, v116
	v_lshl_add_u32 v122, v117, 7, v148
	v_and_b32_e32 v117, 7, v117
	v_sub_u32_e32 v118, 1, v149
	v_xor_b32_e32 v118, v118, v117
	v_lshl_add_u32 v118, v118, 4, v122
	v_sub_u32_e32 v119, 3, v149
	v_xor_b32_e32 v119, v119, v117
	v_lshl_add_u32 v119, v119, 4, v122
	v_sub_u32_e32 v120, 5, v149
	v_xor_b32_e32 v120, v120, v117
	v_lshl_add_u32 v120, v120, 4, v122
	v_sub_u32_e32 v121, 7, v149
	v_xor_b32_e32 v121, v121, v117
	v_lshl_add_u32 v121, v121, 4, v122
	v_lshrrev_b32_e32 v117, 3, v116
	v_and_b32_e32 v149, 7, v116
	v_lshl_add_u32 v122, v117, 7, v148
	v_xor_b32_e32 v148, v149, v117
	v_lshl_add_u32 v122, v148, 4, v122
	v_mul_u32_u24_e32 v144, 0x880, v117
	v_lshl_add_u32 v144, v149, 4, v144
	v_add_u32_e32 v145, 0x4400, v144
	v_add_u32_e32 v146, 0x8800, v144
	v_add_u32_e32 v147, 0xcc00, v144
	v_mbcnt_lo_u32_b32 v108, -1, 0
	v_mbcnt_hi_u32_b32 v108, -1, v108
	v_cmp_gt_u32_e32 vcc, 32, v108
	s_nop 1
	v_cndmask_b32_e64 v109, -1, 0, vcc
	v_cndmask_b32_e64 v108, -8, 16, vcc
	v_mbcnt_lo_u32_b32 v72, -1, 0
	v_mbcnt_hi_u32_b32 v72, -1, v72
	s_movk_i32 s0, 0x100
	v_add_u32_e32 v0, s77, v72
	v_cmp_gt_u32_e32 vcc, s0, v0
	v_mov_b32_e32 v66, s20
	v_mov_b32_e32 v67, s9
	v_cndmask_b32_e32 v70, v66, v67, vcc
	v_mov_b32_e32 v66, s43
	v_mov_b32_e32 v67, s21
	v_cndmask_b32_e32 v66, v66, v67, vcc
	v_and_b32_e32 v0, 0xc0, v0
	v_lshl_or_b32 v0, v66, 8, v0
	v_add_u32_e32 v0, s45, v0
	v_and_or_b32 v75, v72, 31, v0
	v_mov_b32_e32 v0, v151
	s_nop 1
	v_permlane32_swap_b32_e32 v151, v0
	v_mov_b64_e32 v[66:67], s[74:75]
	v_add_f32_e32 v74, v151, v0
	v_mad_u64_u32 v[68:69], s[0:1], v75, s4, v[66:67]
	v_lshlrev_b32_e32 v0, 7, v70
	v_lshrrev_b32_e32 v66, 2, v72
	v_lshl_add_u64 v[70:71], v[68:69], 0, v[0:1]
	v_and_b32_e32 v66, 8, v66
	v_mov_b32_e32 v67, v1
	v_lshl_add_u64 v[70:71], v[70:71], 0, v[66:67]
	s_mov_b64 s[22:23], 0x4400d00
	s_mov_b32 s5, 0x4400000
	v_lshl_add_u64 v[86:87], v[70:71], 0, s[22:23]
	v_add_co_u32_e32 v70, vcc, s5, v70
	v_rcp_f32_e32 v74, v74
	s_nop 0
	v_addc_co_u32_e32 v71, vcc, 0, v71, vcc
	v_lshl_add_u64 v[114:115], v[86:87], 0, v[108:109]
	global_load_dwordx4 v[170:173], v[114:115], off
	global_load_dwordx4 v[174:177], v[114:115], off offset:32
	global_load_dwordx4 v[178:181], v[114:115], off offset:64
	global_load_dwordx4 v[182:185], v[114:115], off offset:96
	v_pk_mul_f32 v[50:51], v[50:51], v[74:75] op_sel_hi:[1,0]
	s_movk_i32 s18, 0xf3c0
	v_mad_u64_u32 v[84:85], s[0:1], v75, s18, v[68:69]
	v_pk_mul_f32 v[52:53], v[52:53], v[74:75] op_sel_hi:[1,0]
	v_sub_u32_e32 v85, v85, v75
	v_lshl_add_u64 v[84:85], v[84:85], 0, v[0:1]
	v_pk_mul_f32 v[54:55], v[54:55], v[74:75] op_sel_hi:[1,0]
	v_pk_mul_f32 v[56:57], v[56:57], v[74:75] op_sel_hi:[1,0]
	v_pk_mul_f32 v[34:35], v[34:35], v[74:75] op_sel_hi:[1,0]
	v_pk_mul_f32 v[36:37], v[36:37], v[74:75] op_sel_hi:[1,0]
	v_pk_mul_f32 v[38:39], v[38:39], v[74:75] op_sel_hi:[1,0]
	v_pk_mul_f32 v[40:41], v[40:41], v[74:75] op_sel_hi:[1,0]
	s_mov_b64 s[0:1], 0x29800
	s_waitcnt vmcnt(3)
	v_permlane32_swap_b32_e32 v170, v172
	v_permlane32_swap_b32_e32 v171, v173
	v_mov_b32_e32 v90, v170
	v_mov_b32_e32 v91, v171
	v_mov_b32_e32 v88, v172
	v_mov_b32_e32 v89, v173
	v_lshlrev_b32_e32 v86, 16, v88
	v_and_b32_e32 v87, 0xffff0000, v88
	v_mul_f32_e32 v88, 0xbfb8aa3b, v86
	v_exp_f32_e32 v88, v88
	s_nop 0
	v_add_f32_e32 v88, 1.0, v88
	v_rcp_f32_e32 v92, v88
	v_mul_f32_e32 v88, 0xbfb8aa3b, v87
	v_exp_f32_e32 v88, v88
	s_nop 0
	v_add_f32_e32 v88, 1.0, v88
	v_rcp_f32_e32 v93, v88
	s_nop 0
	v_pk_mul_f32 v[86:87], v[92:93], v[86:87]
	s_nop 0
	v_pk_mul_f32 v[50:51], v[50:51], v[86:87]
	v_lshlrev_b32_e32 v86, 16, v89
	v_and_b32_e32 v87, 0xffff0000, v89
	v_mul_f32_e32 v88, 0xbfb8aa3b, v86
	v_mul_f32_e32 v89, 0xbfb8aa3b, v87
	v_exp_f32_e32 v88, v88
	v_exp_f32_e32 v89, v89
	v_add_f32_e32 v88, 1.0, v88
	v_add_f32_e32 v89, 1.0, v89
	v_rcp_f32_e32 v88, v88
	v_rcp_f32_e32 v89, v89
	s_nop 0
	v_pk_mul_f32 v[86:87], v[88:89], v[86:87]
	s_nop 0
	v_pk_mul_f32 v[52:53], v[52:53], v[86:87]
	v_cvt_pk_bf16_f32 v86, v50, v51
	v_cvt_pk_bf16_f32 v87, v52, v53
	s_waitcnt vmcnt(3)
	v_lshlrev_b32_e32 v52, 16, v90
	v_and_b32_e32 v53, 0xffff0000, v90
	v_lshl_add_u64 v[50:51], v[84:85], 0, v[66:67]
	v_mul_f32_e32 v84, 0xbfb8aa3b, v52
	v_mul_f32_e32 v85, 0xbfb8aa3b, v53
	v_exp_f32_e32 v84, v84
	v_exp_f32_e32 v85, v85
	v_mov_b32_e32 v106, v86
	v_mov_b32_e32 v107, v87
	v_add_f32_e32 v84, 1.0, v84
	v_add_f32_e32 v85, 1.0, v85
	v_rcp_f32_e32 v84, v84
	v_rcp_f32_e32 v85, v85
	s_nop 0
	v_pk_mul_f32 v[52:53], v[84:85], v[52:53]
	s_nop 0
	v_pk_mul_f32 v[52:53], v[54:55], v[52:53]
	v_lshlrev_b32_e32 v54, 16, v91
	v_and_b32_e32 v55, 0xffff0000, v91
	v_mul_f32_e32 v84, 0xbfb8aa3b, v54
	v_mul_f32_e32 v85, 0xbfb8aa3b, v55
	v_exp_f32_e32 v84, v84
	v_exp_f32_e32 v85, v85
	v_cvt_pk_bf16_f32 v52, v52, v53
	v_add_f32_e32 v84, 1.0, v84
	v_add_f32_e32 v85, 1.0, v85
	v_rcp_f32_e32 v84, v84
	v_rcp_f32_e32 v85, v85
	s_nop 0
	v_pk_mul_f32 v[54:55], v[84:85], v[54:55]
	s_nop 0
	v_pk_mul_f32 v[54:55], v[56:57], v[54:55]
	v_pk_mul_f32 v[56:57], v[58:59], v[74:75] op_sel_hi:[1,0]
	v_cvt_pk_bf16_f32 v53, v54, v55
	v_readfirstlane_b32 s98, v50
	v_readfirstlane_b32 s99, v51
	v_mov_b32_e32 v104, v52
	v_mov_b32_e32 v105, v53
	s_nop 1
	v_permlane32_swap_b32_e32 v104, v106
	v_permlane32_swap_b32_e32 v105, v107
	ds_write_b128 v118, v[104:107]
	s_waitcnt vmcnt(2)
	v_permlane32_swap_b32_e32 v174, v176
	v_permlane32_swap_b32_e32 v175, v177
	v_mov_b32_e32 v80, v174
	v_mov_b32_e32 v81, v175
	v_mov_b32_e32 v82, v176
	v_mov_b32_e32 v83, v177
	v_lshlrev_b32_e32 v52, 16, v82
	v_and_b32_e32 v53, 0xffff0000, v82
	v_mul_f32_e32 v54, 0xbfb8aa3b, v52
	v_mul_f32_e32 v55, 0xbfb8aa3b, v53
	v_exp_f32_e32 v54, v54
	v_exp_f32_e32 v55, v55
	v_pk_mul_f32 v[58:59], v[60:61], v[74:75] op_sel_hi:[1,0]
	v_add_f32_e32 v54, 1.0, v54
	v_add_f32_e32 v55, 1.0, v55
	v_rcp_f32_e32 v54, v54
	v_rcp_f32_e32 v55, v55
	s_nop 0
	v_pk_mul_f32 v[52:53], v[54:55], v[52:53]
	v_lshlrev_b32_e32 v54, 16, v83
	v_and_b32_e32 v55, 0xffff0000, v83
	v_pk_mul_f32 v[52:53], v[56:57], v[52:53]
	v_mul_f32_e32 v56, 0xbfb8aa3b, v54
	v_mul_f32_e32 v57, 0xbfb8aa3b, v55
	v_exp_f32_e32 v56, v56
	v_exp_f32_e32 v57, v57
	v_cvt_pk_bf16_f32 v52, v52, v53
	v_add_f32_e32 v56, 1.0, v56
	v_add_f32_e32 v57, 1.0, v57
	v_rcp_f32_e32 v56, v56
	v_rcp_f32_e32 v57, v57
	s_nop 0
	v_pk_mul_f32 v[54:55], v[56:57], v[54:55]
	s_nop 0
	v_pk_mul_f32 v[54:55], v[58:59], v[54:55]
	v_pk_mul_f32 v[56:57], v[62:63], v[74:75] op_sel_hi:[1,0]
	v_cvt_pk_bf16_f32 v53, v54, v55
	v_mov_b32_e32 v106, v52
	v_mov_b32_e32 v107, v53
	s_waitcnt vmcnt(2)
	v_lshlrev_b32_e32 v52, 16, v80
	v_and_b32_e32 v53, 0xffff0000, v80
	v_mul_f32_e32 v54, 0xbfb8aa3b, v52
	v_mul_f32_e32 v55, 0xbfb8aa3b, v53
	v_exp_f32_e32 v54, v54
	v_exp_f32_e32 v55, v55
	v_pk_mul_f32 v[58:59], v[64:65], v[74:75] op_sel_hi:[1,0]
	v_add_f32_e32 v54, 1.0, v54
	v_add_f32_e32 v55, 1.0, v55
	v_rcp_f32_e32 v54, v54
	v_rcp_f32_e32 v55, v55
	s_nop 0
	v_pk_mul_f32 v[52:53], v[54:55], v[52:53]
	v_lshlrev_b32_e32 v54, 16, v81
	v_and_b32_e32 v55, 0xffff0000, v81
	v_pk_mul_f32 v[52:53], v[56:57], v[52:53]
	v_mul_f32_e32 v56, 0xbfb8aa3b, v54
	v_mul_f32_e32 v57, 0xbfb8aa3b, v55
	v_exp_f32_e32 v56, v56
	v_exp_f32_e32 v57, v57
	v_cvt_pk_bf16_f32 v52, v52, v53
	v_add_f32_e32 v56, 1.0, v56
	v_add_f32_e32 v57, 1.0, v57
	v_rcp_f32_e32 v56, v56
	v_rcp_f32_e32 v57, v57
	s_nop 0
	v_pk_mul_f32 v[54:55], v[56:57], v[54:55]
	s_nop 0
	v_pk_mul_f32 v[54:55], v[58:59], v[54:55]
	s_nop 0
	v_cvt_pk_bf16_f32 v53, v54, v55
	v_mov_b32_e32 v104, v52
	v_mov_b32_e32 v105, v53
	s_nop 1
	v_permlane32_swap_b32_e32 v104, v106
	v_permlane32_swap_b32_e32 v105, v107
	ds_write_b128 v119, v[104:107]
	s_waitcnt vmcnt(1)
	v_permlane32_swap_b32_e32 v178, v180
	v_permlane32_swap_b32_e32 v179, v181
	v_mov_b32_e32 v76, v178
	v_mov_b32_e32 v77, v179
	v_mov_b32_e32 v78, v180
	v_mov_b32_e32 v79, v181
	v_lshlrev_b32_e32 v52, 16, v78
	v_and_b32_e32 v53, 0xffff0000, v78
	v_mul_f32_e32 v54, 0xbfb8aa3b, v52
	v_mul_f32_e32 v55, 0xbfb8aa3b, v53
	v_exp_f32_e32 v54, v54
	v_exp_f32_e32 v55, v55
	v_add_f32_e32 v54, 1.0, v54
	v_add_f32_e32 v55, 1.0, v55
	v_rcp_f32_e32 v54, v54
	v_rcp_f32_e32 v55, v55
	s_nop 0
	v_pk_mul_f32 v[52:53], v[54:55], v[52:53]
	s_nop 0
	v_pk_mul_f32 v[34:35], v[34:35], v[52:53]
	v_lshlrev_b32_e32 v52, 16, v79
	v_and_b32_e32 v53, 0xffff0000, v79
	v_mul_f32_e32 v54, 0xbfb8aa3b, v52
	v_mul_f32_e32 v55, 0xbfb8aa3b, v53
	v_exp_f32_e32 v54, v54
	v_exp_f32_e32 v55, v55
	v_cvt_pk_bf16_f32 v34, v34, v35
	v_add_f32_e32 v54, 1.0, v54
	v_add_f32_e32 v55, 1.0, v55
	v_rcp_f32_e32 v54, v54
	v_rcp_f32_e32 v55, v55
	s_nop 0
	v_pk_mul_f32 v[52:53], v[54:55], v[52:53]
	s_nop 0
	v_pk_mul_f32 v[36:37], v[36:37], v[52:53]
	s_nop 0
	v_cvt_pk_bf16_f32 v35, v36, v37
	v_mov_b32_e32 v106, v34
	v_mov_b32_e32 v107, v35
	s_waitcnt vmcnt(1)
	v_lshlrev_b32_e32 v34, 16, v76
	v_and_b32_e32 v35, 0xffff0000, v76
	v_mul_f32_e32 v36, 0xbfb8aa3b, v34
	v_mul_f32_e32 v37, 0xbfb8aa3b, v35
	v_exp_f32_e32 v36, v36
	v_exp_f32_e32 v37, v37
	v_add_f32_e32 v36, 1.0, v36
	v_add_f32_e32 v37, 1.0, v37
	v_rcp_f32_e32 v36, v36
	v_rcp_f32_e32 v37, v37
	s_nop 0
	v_pk_mul_f32 v[34:35], v[36:37], v[34:35]
	v_lshlrev_b32_e32 v36, 16, v77
	v_and_b32_e32 v37, 0xffff0000, v77
	v_pk_mul_f32 v[34:35], v[38:39], v[34:35]
	v_mul_f32_e32 v38, 0xbfb8aa3b, v36
	v_mul_f32_e32 v39, 0xbfb8aa3b, v37
	v_exp_f32_e32 v38, v38
	v_exp_f32_e32 v39, v39
	v_cvt_pk_bf16_f32 v34, v34, v35
	v_add_f32_e32 v38, 1.0, v38
	v_add_f32_e32 v39, 1.0, v39
	v_rcp_f32_e32 v38, v38
	v_rcp_f32_e32 v39, v39
	s_nop 0
	v_pk_mul_f32 v[36:37], v[38:39], v[36:37]
	s_nop 0
	v_pk_mul_f32 v[36:37], v[40:41], v[36:37]
	v_pk_mul_f32 v[38:39], v[42:43], v[74:75] op_sel_hi:[1,0]
	v_cvt_pk_bf16_f32 v35, v36, v37
	v_mov_b32_e32 v104, v34
	v_mov_b32_e32 v105, v35
	s_nop 1
	v_permlane32_swap_b32_e32 v104, v106
	v_permlane32_swap_b32_e32 v105, v107
	ds_write_b128 v120, v[104:107]
	s_waitcnt vmcnt(0)
	v_permlane32_swap_b32_e32 v182, v184
	v_permlane32_swap_b32_e32 v183, v185
	v_mov_b32_e32 v70, v182
	v_mov_b32_e32 v71, v183
	v_mov_b32_e32 v72, v184
	v_mov_b32_e32 v73, v185
	v_lshlrev_b32_e32 v34, 16, v72
	v_and_b32_e32 v35, 0xffff0000, v72
	v_mul_f32_e32 v36, 0xbfb8aa3b, v34
	v_mul_f32_e32 v37, 0xbfb8aa3b, v35
	v_exp_f32_e32 v36, v36
	v_exp_f32_e32 v37, v37
	v_pk_mul_f32 v[40:41], v[44:45], v[74:75] op_sel_hi:[1,0]
	v_add_f32_e32 v36, 1.0, v36
	v_add_f32_e32 v37, 1.0, v37
	v_rcp_f32_e32 v36, v36
	v_rcp_f32_e32 v37, v37
	s_nop 0
	v_pk_mul_f32 v[34:35], v[36:37], v[34:35]
	v_lshlrev_b32_e32 v36, 16, v73
	v_and_b32_e32 v37, 0xffff0000, v73
	v_pk_mul_f32 v[34:35], v[38:39], v[34:35]
	v_mul_f32_e32 v38, 0xbfb8aa3b, v36
	v_mul_f32_e32 v39, 0xbfb8aa3b, v37
	v_exp_f32_e32 v38, v38
	v_exp_f32_e32 v39, v39
	v_cvt_pk_bf16_f32 v34, v34, v35
	v_add_f32_e32 v38, 1.0, v38
	v_add_f32_e32 v39, 1.0, v39
	v_rcp_f32_e32 v38, v38
	v_rcp_f32_e32 v39, v39
	s_nop 0
	v_pk_mul_f32 v[36:37], v[38:39], v[36:37]
	s_nop 0
	v_pk_mul_f32 v[36:37], v[40:41], v[36:37]
	v_pk_mul_f32 v[38:39], v[46:47], v[74:75] op_sel_hi:[1,0]
	v_cvt_pk_bf16_f32 v35, v36, v37
	v_mov_b32_e32 v106, v34
	v_mov_b32_e32 v107, v35
	s_waitcnt vmcnt(0)
	v_lshlrev_b32_e32 v34, 16, v70
	v_and_b32_e32 v35, 0xffff0000, v70
	v_mul_f32_e32 v36, 0xbfb8aa3b, v34
	v_mul_f32_e32 v37, 0xbfb8aa3b, v35
	v_exp_f32_e32 v36, v36
	v_exp_f32_e32 v37, v37
	v_pk_mul_f32 v[40:41], v[48:49], v[74:75] op_sel_hi:[1,0]
	v_add_f32_e32 v36, 1.0, v36
	v_add_f32_e32 v37, 1.0, v37
	v_rcp_f32_e32 v36, v36
	v_rcp_f32_e32 v37, v37
	s_nop 0
	v_pk_mul_f32 v[34:35], v[36:37], v[34:35]
	v_lshlrev_b32_e32 v36, 16, v71
	v_and_b32_e32 v37, 0xffff0000, v71
	v_pk_mul_f32 v[34:35], v[38:39], v[34:35]
	v_mul_f32_e32 v38, 0xbfb8aa3b, v36
	v_mul_f32_e32 v39, 0xbfb8aa3b, v37
	v_exp_f32_e32 v38, v38
	v_exp_f32_e32 v39, v39
	v_cvt_pk_bf16_f32 v34, v34, v35
	v_add_f32_e32 v38, 1.0, v38
	v_add_f32_e32 v39, 1.0, v39
	v_rcp_f32_e32 v38, v38
	v_rcp_f32_e32 v39, v39
	s_nop 0
	v_pk_mul_f32 v[36:37], v[38:39], v[36:37]
	s_nop 0
	v_pk_mul_f32 v[36:37], v[40:41], v[36:37]
	v_or_b32_e32 v38, 32, v75
	v_cvt_pk_bf16_f32 v35, v36, v37
	v_mov_b32_e32 v104, v34
	v_mov_b32_e32 v105, v35
	s_nop 1
	v_permlane32_swap_b32_e32 v104, v106
	v_permlane32_swap_b32_e32 v105, v107
	ds_write_b128 v121, v[104:107]
	ds_read_b128 v[124:127], v122
	ds_read_b128 v[128:131], v122 offset:1024
	ds_read_b128 v[132:135], v122 offset:2048
	ds_read_b128 v[136:139], v122 offset:3072
	s_waitcnt lgkmcnt(3)
	global_store_dwordx4 v144, v[124:127], s[98:99] offset:768 sc0 sc1
	s_waitcnt lgkmcnt(2)
	global_store_dwordx4 v145, v[128:131], s[98:99] offset:768 sc0 sc1
	s_waitcnt lgkmcnt(1)
	global_store_dwordx4 v146, v[132:135], s[98:99] offset:768 sc0 sc1
	s_waitcnt lgkmcnt(0)
	global_store_dwordx4 v147, v[136:139], s[98:99] offset:768 sc0 sc1
	v_mov_b32_e32 v34, v150
	s_nop 1
	v_permlane32_swap_b32_e32 v150, v34
	v_add_f32_e32 v54, v150, v34
	v_lshl_add_u64 v[34:35], v[68:69], 0, s[0:1]
	v_lshl_add_u64 v[36:37], v[34:35], 0, v[0:1]
	v_lshl_add_u64 v[36:37], v[36:37], 0, v[66:67]
	v_mad_u64_u32 v[52:53], s[0:1], v38, s18, v[34:35]
	v_lshl_add_u64 v[34:35], v[36:37], 0, s[22:23]
	v_add_co_u32_e32 v36, vcc, s5, v36
	v_sub_u32_e32 v53, v53, v38
	s_nop 0
	v_addc_co_u32_e32 v37, vcc, 0, v37, vcc
	v_lshl_add_u64 v[116:117], v[34:35], 0, v[108:109]
	global_load_dwordx4 v[186:189], v[116:117], off
	global_load_dwordx4 v[190:193], v[116:117], off offset:32
	global_load_dwordx4 v[194:197], v[116:117], off offset:64
	global_load_dwordx4 v[198:201], v[116:117], off offset:96
	v_rcp_f32_e32 v34, v54
	v_lshl_add_u64 v[52:53], v[52:53], 0, v[0:1]
	s_mov_b64 s[0:1], 0
	v_pk_mul_f32 v[18:19], v[18:19], v[34:35] op_sel_hi:[1,0]
	v_pk_mul_f32 v[20:21], v[20:21], v[34:35] op_sel_hi:[1,0]
	v_pk_mul_f32 v[22:23], v[22:23], v[34:35] op_sel_hi:[1,0]
	v_pk_mul_f32 v[24:25], v[24:25], v[34:35] op_sel_hi:[1,0]
	v_pk_mul_f32 v[2:3], v[2:3], v[34:35] op_sel_hi:[1,0]
	v_pk_mul_f32 v[4:5], v[4:5], v[34:35] op_sel_hi:[1,0]
	v_pk_mul_f32 v[6:7], v[6:7], v[34:35] op_sel_hi:[1,0]
	v_pk_mul_f32 v[8:9], v[8:9], v[34:35] op_sel_hi:[1,0]
	s_waitcnt vmcnt(3)
	v_permlane32_swap_b32_e32 v186, v188
	v_permlane32_swap_b32_e32 v187, v189
	v_mov_b32_e32 v48, v186
	v_mov_b32_e32 v49, v187
	v_mov_b32_e32 v50, v188
	v_mov_b32_e32 v51, v189
	v_lshlrev_b32_e32 v54, 16, v50
	v_mul_f32_e32 v0, 0xbfb8aa3b, v54
	v_exp_f32_e32 v0, v0
	v_and_b32_e32 v55, 0xffff0000, v50
	v_lshlrev_b32_e32 v50, 16, v51
	v_and_b32_e32 v51, 0xffff0000, v51
	v_add_f32_e32 v0, 1.0, v0
	v_rcp_f32_e32 v56, v0
	v_mul_f32_e32 v0, 0xbfb8aa3b, v55
	v_exp_f32_e32 v0, v0
	s_nop 0
	v_add_f32_e32 v0, 1.0, v0
	v_rcp_f32_e32 v57, v0
	v_mul_f32_e32 v0, 0xbfb8aa3b, v50
	v_exp_f32_e32 v0, v0
	v_pk_mul_f32 v[54:55], v[56:57], v[54:55]
	s_nop 0
	v_pk_mul_f32 v[18:19], v[18:19], v[54:55]
	v_add_f32_e32 v0, 1.0, v0
	v_rcp_f32_e32 v54, v0
	v_mul_f32_e32 v0, 0xbfb8aa3b, v51
	v_exp_f32_e32 v0, v0
	s_nop 0
	v_add_f32_e32 v0, 1.0, v0
	v_rcp_f32_e32 v55, v0
	s_nop 0
	v_pk_mul_f32 v[50:51], v[54:55], v[50:51]
	s_nop 0
	v_pk_mul_f32 v[20:21], v[20:21], v[50:51]
	v_cvt_pk_bf16_f32 v50, v18, v19
	v_cvt_pk_bf16_f32 v51, v20, v21
	s_waitcnt vmcnt(3)
	v_lshlrev_b32_e32 v20, 16, v48
	v_mul_f32_e32 v0, 0xbfb8aa3b, v20
	v_exp_f32_e32 v0, v0
	v_lshl_add_u64 v[18:19], v[52:53], 0, v[66:67]
	v_and_b32_e32 v21, 0xffff0000, v48
	v_mov_b32_e32 v106, v50
	v_mov_b32_e32 v107, v51
	v_add_f32_e32 v0, 1.0, v0
	v_rcp_f32_e32 v50, v0
	v_mul_f32_e32 v0, 0xbfb8aa3b, v21
	v_exp_f32_e32 v0, v0
	s_nop 0
	v_add_f32_e32 v0, 1.0, v0
	v_rcp_f32_e32 v51, v0
	s_nop 0
	v_pk_mul_f32 v[20:21], v[50:51], v[20:21]
	s_nop 0
	v_pk_mul_f32 v[20:21], v[22:23], v[20:21]
	v_lshlrev_b32_e32 v22, 16, v49
	v_mul_f32_e32 v0, 0xbfb8aa3b, v22
	v_exp_f32_e32 v0, v0
	v_and_b32_e32 v23, 0xffff0000, v49
	v_cvt_pk_bf16_f32 v20, v20, v21
	v_add_f32_e32 v0, 1.0, v0
	v_rcp_f32_e32 v48, v0
	v_mul_f32_e32 v0, 0xbfb8aa3b, v23
	v_exp_f32_e32 v0, v0
	s_nop 0
	v_add_f32_e32 v0, 1.0, v0
	v_rcp_f32_e32 v49, v0
	s_nop 0
	v_pk_mul_f32 v[22:23], v[48:49], v[22:23]
	s_nop 0
	v_pk_mul_f32 v[22:23], v[24:25], v[22:23]
	v_pk_mul_f32 v[24:25], v[26:27], v[34:35] op_sel_hi:[1,0]
	v_cvt_pk_bf16_f32 v21, v22, v23
	v_readfirstlane_b32 s98, v18
	v_readfirstlane_b32 s99, v19
	v_mov_b32_e32 v104, v20
	v_mov_b32_e32 v105, v21
	s_nop 1
	v_permlane32_swap_b32_e32 v104, v106
	v_permlane32_swap_b32_e32 v105, v107
	ds_write_b128 v118, v[104:107]
	s_waitcnt vmcnt(2)
	v_permlane32_swap_b32_e32 v190, v192
	v_permlane32_swap_b32_e32 v191, v193
	v_mov_b32_e32 v44, v190
	v_mov_b32_e32 v45, v191
	v_mov_b32_e32 v46, v192
	v_mov_b32_e32 v47, v193
	v_lshlrev_b32_e32 v20, 16, v46
	v_mul_f32_e32 v0, 0xbfb8aa3b, v20
	v_exp_f32_e32 v0, v0
	v_and_b32_e32 v21, 0xffff0000, v46
	v_pk_mul_f32 v[26:27], v[28:29], v[34:35] op_sel_hi:[1,0]
	v_add_f32_e32 v0, 1.0, v0
	v_rcp_f32_e32 v22, v0
	v_mul_f32_e32 v0, 0xbfb8aa3b, v21
	v_exp_f32_e32 v0, v0
	s_nop 0
	v_add_f32_e32 v0, 1.0, v0
	v_rcp_f32_e32 v23, v0
	s_nop 0
	v_pk_mul_f32 v[20:21], v[22:23], v[20:21]
	v_lshlrev_b32_e32 v22, 16, v47
	v_mul_f32_e32 v0, 0xbfb8aa3b, v22
	v_exp_f32_e32 v0, v0
	v_and_b32_e32 v23, 0xffff0000, v47
	v_pk_mul_f32 v[20:21], v[24:25], v[20:21]
	v_add_f32_e32 v0, 1.0, v0
	v_rcp_f32_e32 v24, v0
	v_mul_f32_e32 v0, 0xbfb8aa3b, v23
	v_exp_f32_e32 v0, v0
	v_cvt_pk_bf16_f32 v20, v20, v21
	v_add_f32_e32 v0, 1.0, v0
	v_rcp_f32_e32 v25, v0
	s_nop 0
	v_pk_mul_f32 v[22:23], v[24:25], v[22:23]
	s_nop 0
	v_pk_mul_f32 v[22:23], v[26:27], v[22:23]
	v_pk_mul_f32 v[24:25], v[30:31], v[34:35] op_sel_hi:[1,0]
	v_cvt_pk_bf16_f32 v21, v22, v23
	v_mov_b32_e32 v106, v20
	v_mov_b32_e32 v107, v21
	s_waitcnt vmcnt(2)
	v_lshlrev_b32_e32 v20, 16, v44
	v_mul_f32_e32 v0, 0xbfb8aa3b, v20
	v_exp_f32_e32 v0, v0
	v_and_b32_e32 v21, 0xffff0000, v44
	v_pk_mul_f32 v[26:27], v[32:33], v[34:35] op_sel_hi:[1,0]
	v_add_f32_e32 v0, 1.0, v0
	v_rcp_f32_e32 v22, v0
	v_mul_f32_e32 v0, 0xbfb8aa3b, v21
	v_exp_f32_e32 v0, v0
	s_nop 0
	v_add_f32_e32 v0, 1.0, v0
	v_rcp_f32_e32 v23, v0
	s_nop 0
	v_pk_mul_f32 v[20:21], v[22:23], v[20:21]
	v_lshlrev_b32_e32 v22, 16, v45
	v_mul_f32_e32 v0, 0xbfb8aa3b, v22
	v_exp_f32_e32 v0, v0
	v_and_b32_e32 v23, 0xffff0000, v45
	v_pk_mul_f32 v[20:21], v[24:25], v[20:21]
	v_add_f32_e32 v0, 1.0, v0
	v_rcp_f32_e32 v24, v0
	v_mul_f32_e32 v0, 0xbfb8aa3b, v23
	v_exp_f32_e32 v0, v0
	v_cvt_pk_bf16_f32 v20, v20, v21
	v_add_f32_e32 v0, 1.0, v0
	v_rcp_f32_e32 v25, v0
	s_nop 0
	v_pk_mul_f32 v[22:23], v[24:25], v[22:23]
	s_nop 0
	v_pk_mul_f32 v[22:23], v[26:27], v[22:23]
	s_nop 0
	v_cvt_pk_bf16_f32 v21, v22, v23
	v_mov_b32_e32 v104, v20
	v_mov_b32_e32 v105, v21
	s_nop 1
	v_permlane32_swap_b32_e32 v104, v106
	v_permlane32_swap_b32_e32 v105, v107
	ds_write_b128 v119, v[104:107]
	s_waitcnt vmcnt(1)
	v_permlane32_swap_b32_e32 v194, v196
	v_permlane32_swap_b32_e32 v195, v197
	v_mov_b32_e32 v40, v194
	v_mov_b32_e32 v41, v195
	v_mov_b32_e32 v42, v196
	v_mov_b32_e32 v43, v197
	v_lshlrev_b32_e32 v20, 16, v42
	v_mul_f32_e32 v0, 0xbfb8aa3b, v20
	v_exp_f32_e32 v0, v0
	v_and_b32_e32 v21, 0xffff0000, v42
	v_add_f32_e32 v0, 1.0, v0
	v_rcp_f32_e32 v22, v0
	v_mul_f32_e32 v0, 0xbfb8aa3b, v21
	v_exp_f32_e32 v0, v0
	s_nop 0
	v_add_f32_e32 v0, 1.0, v0
	v_rcp_f32_e32 v23, v0
	s_nop 0
	v_pk_mul_f32 v[20:21], v[22:23], v[20:21]
	s_nop 0
	v_pk_mul_f32 v[2:3], v[2:3], v[20:21]
	v_lshlrev_b32_e32 v20, 16, v43
	v_mul_f32_e32 v0, 0xbfb8aa3b, v20
	v_exp_f32_e32 v0, v0
	v_and_b32_e32 v21, 0xffff0000, v43
	v_cvt_pk_bf16_f32 v2, v2, v3
	v_add_f32_e32 v0, 1.0, v0
	v_rcp_f32_e32 v22, v0
	v_mul_f32_e32 v0, 0xbfb8aa3b, v21
	v_exp_f32_e32 v0, v0
	s_nop 0
	v_add_f32_e32 v0, 1.0, v0
	v_rcp_f32_e32 v23, v0
	s_nop 0
	v_pk_mul_f32 v[20:21], v[22:23], v[20:21]
	s_nop 0
	v_pk_mul_f32 v[4:5], v[4:5], v[20:21]
	s_nop 0
	v_cvt_pk_bf16_f32 v3, v4, v5
	v_mov_b32_e32 v106, v2
	v_mov_b32_e32 v107, v3
	s_waitcnt vmcnt(1)
	v_lshlrev_b32_e32 v2, 16, v40
	v_mul_f32_e32 v0, 0xbfb8aa3b, v2
	v_exp_f32_e32 v0, v0
	v_and_b32_e32 v3, 0xffff0000, v40
	v_add_f32_e32 v0, 1.0, v0
	v_rcp_f32_e32 v4, v0
	v_mul_f32_e32 v0, 0xbfb8aa3b, v3
	v_exp_f32_e32 v0, v0
	s_nop 0
	v_add_f32_e32 v0, 1.0, v0
	v_rcp_f32_e32 v5, v0
	s_nop 0
	v_pk_mul_f32 v[2:3], v[4:5], v[2:3]
	v_lshlrev_b32_e32 v4, 16, v41
	v_mul_f32_e32 v0, 0xbfb8aa3b, v4
	v_exp_f32_e32 v0, v0
	v_and_b32_e32 v5, 0xffff0000, v41
	v_pk_mul_f32 v[2:3], v[6:7], v[2:3]
	v_add_f32_e32 v0, 1.0, v0
	v_rcp_f32_e32 v6, v0
	v_mul_f32_e32 v0, 0xbfb8aa3b, v5
	v_exp_f32_e32 v0, v0
	v_cvt_pk_bf16_f32 v2, v2, v3
	v_add_f32_e32 v0, 1.0, v0
	v_rcp_f32_e32 v7, v0
	s_nop 0
	v_pk_mul_f32 v[4:5], v[6:7], v[4:5]
	s_nop 0
	v_pk_mul_f32 v[4:5], v[8:9], v[4:5]
	v_pk_mul_f32 v[6:7], v[10:11], v[34:35] op_sel_hi:[1,0]
	v_cvt_pk_bf16_f32 v3, v4, v5
	v_mov_b32_e32 v104, v2
	v_mov_b32_e32 v105, v3
	s_nop 1
	v_permlane32_swap_b32_e32 v104, v106
	v_permlane32_swap_b32_e32 v105, v107
	ds_write_b128 v120, v[104:107]
	s_waitcnt vmcnt(0)
	v_permlane32_swap_b32_e32 v198, v200
	v_permlane32_swap_b32_e32 v199, v201
	v_mov_b32_e32 v36, v198
	v_mov_b32_e32 v37, v199
	v_mov_b32_e32 v38, v200
	v_mov_b32_e32 v39, v201
	v_lshlrev_b32_e32 v2, 16, v38
	v_mul_f32_e32 v0, 0xbfb8aa3b, v2
	v_exp_f32_e32 v0, v0
	v_and_b32_e32 v3, 0xffff0000, v38
	v_pk_mul_f32 v[8:9], v[12:13], v[34:35] op_sel_hi:[1,0]
	v_add_f32_e32 v0, 1.0, v0
	v_rcp_f32_e32 v4, v0
	v_mul_f32_e32 v0, 0xbfb8aa3b, v3
	v_exp_f32_e32 v0, v0
	s_nop 0
	v_add_f32_e32 v0, 1.0, v0
	v_rcp_f32_e32 v5, v0
	s_nop 0
	v_pk_mul_f32 v[2:3], v[4:5], v[2:3]
	v_lshlrev_b32_e32 v4, 16, v39
	v_mul_f32_e32 v0, 0xbfb8aa3b, v4
	v_exp_f32_e32 v0, v0
	v_and_b32_e32 v5, 0xffff0000, v39
	v_pk_mul_f32 v[2:3], v[6:7], v[2:3]
	v_add_f32_e32 v0, 1.0, v0
	v_rcp_f32_e32 v6, v0
	v_mul_f32_e32 v0, 0xbfb8aa3b, v5
	v_exp_f32_e32 v0, v0
	v_cvt_pk_bf16_f32 v2, v2, v3
	v_add_f32_e32 v0, 1.0, v0
	v_rcp_f32_e32 v7, v0
	s_nop 0
	v_pk_mul_f32 v[4:5], v[6:7], v[4:5]
	s_nop 0
	v_pk_mul_f32 v[4:5], v[8:9], v[4:5]
	v_pk_mul_f32 v[6:7], v[14:15], v[34:35] op_sel_hi:[1,0]
	v_cvt_pk_bf16_f32 v3, v4, v5
	v_mov_b32_e32 v106, v2
	v_mov_b32_e32 v107, v3
	s_waitcnt vmcnt(0)
	v_lshlrev_b32_e32 v2, 16, v36
	v_mul_f32_e32 v0, 0xbfb8aa3b, v2
	v_exp_f32_e32 v0, v0
	v_and_b32_e32 v3, 0xffff0000, v36
	v_pk_mul_f32 v[8:9], v[16:17], v[34:35] op_sel_hi:[1,0]
	v_add_f32_e32 v0, 1.0, v0
	v_rcp_f32_e32 v4, v0
	v_mul_f32_e32 v0, 0xbfb8aa3b, v3
	v_exp_f32_e32 v0, v0
	s_nop 0
	v_add_f32_e32 v0, 1.0, v0
	v_rcp_f32_e32 v5, v0
	s_nop 0
	v_pk_mul_f32 v[2:3], v[4:5], v[2:3]
	v_lshlrev_b32_e32 v4, 16, v37
	v_mul_f32_e32 v0, 0xbfb8aa3b, v4
	v_exp_f32_e32 v0, v0
	v_and_b32_e32 v5, 0xffff0000, v37
	v_pk_mul_f32 v[2:3], v[6:7], v[2:3]
	v_add_f32_e32 v0, 1.0, v0
	v_rcp_f32_e32 v6, v0
	v_mul_f32_e32 v0, 0xbfb8aa3b, v5
	v_exp_f32_e32 v0, v0
	v_cvt_pk_bf16_f32 v2, v2, v3
	v_add_f32_e32 v0, 1.0, v0
	v_rcp_f32_e32 v7, v0
	s_nop 0
	v_pk_mul_f32 v[4:5], v[6:7], v[4:5]
	s_nop 0
	v_pk_mul_f32 v[4:5], v[8:9], v[4:5]
	s_nop 0
	v_cvt_pk_bf16_f32 v3, v4, v5
	v_mov_b32_e32 v104, v2
	v_mov_b32_e32 v105, v3
	s_nop 1
	v_permlane32_swap_b32_e32 v104, v106
	v_permlane32_swap_b32_e32 v105, v107
	ds_write_b128 v121, v[104:107]
	ds_read_b128 v[124:127], v122
	ds_read_b128 v[128:131], v122 offset:1024
	ds_read_b128 v[132:135], v122 offset:2048
	ds_read_b128 v[136:139], v122 offset:3072
	s_waitcnt lgkmcnt(3)
	global_store_dwordx4 v144, v[124:127], s[98:99] offset:768 sc0 sc1
	s_waitcnt lgkmcnt(2)
	global_store_dwordx4 v145, v[128:131], s[98:99] offset:768 sc0 sc1
	s_waitcnt lgkmcnt(1)
	global_store_dwordx4 v146, v[132:135], s[98:99] offset:768 sc0 sc1
	s_waitcnt lgkmcnt(0)
	global_store_dwordx4 v147, v[136:139], s[98:99] offset:768 sc0 sc1

.LBB0_195:
	s_waitcnt vmcnt(0)
	s_barrier
	v_mbcnt_lo_u32_b32 v116, -1, 0
	v_mbcnt_hi_u32_b32 v116, -1, v116
	v_mov_b32_e32 v148, s77
	v_lshlrev_b32_e32 v148, 6, v148
	v_and_b32_e32 v117, 31, v116
	v_lshrrev_b32_e32 v149, 5, v116
	v_lshl_add_u32 v122, v117, 7, v148
	v_and_b32_e32 v117, 7, v117
	v_sub_u32_e32 v118, 1, v149
	v_xor_b32_e32 v118, v118, v117
	v_lshl_add_u32 v118, v118, 4, v122
	v_sub_u32_e32 v119, 3, v149
	v_xor_b32_e32 v119, v119, v117
	v_lshl_add_u32 v119, v119, 4, v122
	v_sub_u32_e32 v120, 5, v149
	v_xor_b32_e32 v120, v120, v117
	v_lshl_add_u32 v120, v120, 4, v122
	v_sub_u32_e32 v121, 7, v149
	v_xor_b32_e32 v121, v121, v117
	v_lshl_add_u32 v121, v121, 4, v122
	v_lshrrev_b32_e32 v117, 3, v116
	v_and_b32_e32 v149, 7, v116
	v_lshl_add_u32 v122, v117, 7, v148
	v_xor_b32_e32 v148, v149, v117
	v_lshl_add_u32 v122, v148, 4, v122
	v_mul_u32_u24_e32 v144, 0x880, v117
	v_lshl_add_u32 v144, v149, 4, v144
	v_add_u32_e32 v145, 0x4400, v144
	v_add_u32_e32 v146, 0x8800, v144
	v_add_u32_e32 v147, 0xcc00, v144
	v_mbcnt_lo_u32_b32 v108, -1, 0
	v_mbcnt_hi_u32_b32 v108, -1, v108
	v_cmp_gt_u32_e32 vcc, 32, v108
	s_nop 1
	v_cndmask_b32_e64 v109, -1, 0, vcc
	v_cndmask_b32_e64 v108, -8, 16, vcc
	v_mbcnt_lo_u32_b32 v68, -1, 0
	v_mbcnt_hi_u32_b32 v68, -1, v68
	s_movk_i32 s0, 0x100
	v_add_u32_e32 v0, s77, v68
	v_mov_b32_e32 v66, s20
	v_mov_b32_e32 v67, s9
	v_cmp_gt_u32_e32 vcc, s0, v0
	v_mov_b32_e32 v69, s21
	v_and_b32_e32 v0, 0xc0, v0
	v_cndmask_b32_e32 v66, v66, v67, vcc
	v_mov_b32_e32 v67, s43
	v_cndmask_b32_e32 v67, v67, v69, vcc
	v_lshl_or_b32 v0, v67, 8, v0
	v_add_u32_e32 v0, s45, v0
	v_and_or_b32 v82, v68, 31, v0
	v_lshlrev_b32_e32 v0, 7, v66
	v_mov_b64_e32 v[66:67], s[74:75]
	v_mad_u64_u32 v[66:67], s[0:1], v82, s4, v[66:67]
	v_lshrrev_b32_e32 v68, 2, v68
	v_and_b32_e32 v70, 8, v68
	v_mov_b32_e32 v71, v1
	v_lshl_add_u64 v[66:67], v[66:67], 0, v[0:1]
	v_lshl_add_u64 v[68:69], v[66:67], 0, v[70:71]
	v_add_co_u32_e32 v66, vcc, s42, v68
	s_mov_b64 s[0:1], 0x4400600
	s_nop 0
	v_addc_co_u32_e32 v67, vcc, 0, v69, vcc
	v_lshl_add_u64 v[76:77], v[68:69], 0, s[0:1]
	v_lshl_add_u64 v[114:115], v[76:77], 0, v[108:109]
	global_load_dwordx4 v[170:173], v[114:115], off
	v_mov_b32_e32 v66, v251
	s_nop 1
	v_permlane32_swap_b32_e32 v251, v66
	v_add_f32_e32 v66, v251, v66
	v_rcp_f32_e32 v66, v66
	v_lshl_add_u64 v[80:81], s[74:75], 0, v[0:1]
	v_mad_u64_u32 v[80:81], s[0:1], v82, s33, v[80:81]
	v_pk_mul_f32 v[82:83], v[50:51], v[66:67] op_sel_hi:[1,0]
	v_pk_mul_f32 v[84:85], v[52:53], v[66:67] op_sel_hi:[1,0]
	v_pk_mul_f32 v[86:87], v[54:55], v[66:67] op_sel_hi:[1,0]
	v_pk_mul_f32 v[88:89], v[56:57], v[66:67] op_sel_hi:[1,0]
	v_lshl_add_u64 v[50:51], v[80:81], 0, v[70:71]
	global_load_dwordx4 v[174:177], v[114:115], off offset:32
	global_load_dwordx4 v[178:181], v[114:115], off offset:64
	global_load_dwordx4 v[182:185], v[114:115], off offset:96
	s_mov_b32 s0, 0x4429000
	v_mov_b32_e32 v210, 0x358637bd
	v_mov_b32_e32 v211, 0x3e91f4c4
	v_mov_b32_e32 v212, 0x3c0881c4
	v_mov_b32_e32 v213, 0xbab64f3b
	v_xor_b32_e32 v217, 16, v221
	s_waitcnt vmcnt(3)
	v_permlane32_swap_b32_e32 v170, v172
	v_permlane32_swap_b32_e32 v171, v173
	v_mov_b32_e32 v78, v170
	v_mov_b32_e32 v79, v171
	v_mov_b32_e32 v74, v172
	v_mov_b32_e32 v75, v173
	v_lshlrev_b32_e32 v76, 16, v74
	v_and_b32_e32 v77, 0xffff0000, v74
	v_lshlrev_b32_e32 v74, 16, v75
	v_and_b32_e32 v75, 0xffff0000, v75
	s_waitcnt vmcnt(3)
	v_lshlrev_b32_e32 v90, 16, v78
	v_and_b32_e32 v91, 0xffff0000, v78
	v_lshlrev_b32_e32 v78, 16, v79
	v_and_b32_e32 v79, 0xffff0000, v79
	v_mul_f32_e32 v0, 0xbfb8aa3b, v76
	v_mul_f32_e32 v67, 0xbfb8aa3b, v77
	v_mul_f32_e32 v93, 0xbfb8aa3b, v74
	v_mul_f32_e32 v94, 0xbfb8aa3b, v75
	v_mul_f32_e32 v95, 0xbfb8aa3b, v90
	v_mul_f32_e32 v96, 0xbfb8aa3b, v91
	v_mul_f32_e32 v97, 0xbfb8aa3b, v78
	v_mul_f32_e32 v98, 0xbfb8aa3b, v79
	v_exp_f32_e32 v0, v0
	v_exp_f32_e32 v67, v67
	v_exp_f32_e32 v93, v93
	v_exp_f32_e32 v94, v94
	v_exp_f32_e32 v95, v95
	v_exp_f32_e32 v96, v96
	v_exp_f32_e32 v97, v97
	v_exp_f32_e32 v98, v98
	v_add_f32_e32 v0, 1.0, v0
	v_add_f32_e32 v67, 1.0, v67
	v_add_f32_e32 v93, 1.0, v93
	v_add_f32_e32 v99, 1.0, v94
	v_add_f32_e32 v100, 1.0, v95
	v_add_f32_e32 v101, 1.0, v96
	v_add_f32_e32 v102, 1.0, v97
	v_add_f32_e32 v103, 1.0, v98
	v_rcp_f32_e32 v94, v0
	v_rcp_f32_e32 v95, v67
	v_rcp_f32_e32 v96, v93
	v_rcp_f32_e32 v97, v99
	v_rcp_f32_e32 v98, v100
	v_rcp_f32_e32 v99, v101
	s_waitcnt vmcnt(2)
	v_permlane32_swap_b32_e32 v174, v176
	v_permlane32_swap_b32_e32 v175, v177
	v_mov_b32_e32 v80, v174
	v_mov_b32_e32 v81, v175
	v_mov_b32_e32 v72, v176
	v_mov_b32_e32 v73, v177
	v_lshlrev_b32_e32 v92, 16, v72
	v_rcp_f32_e32 v100, v102
	v_rcp_f32_e32 v101, v103
	v_mul_f32_e32 v0, 0xbfb8aa3b, v92
	v_and_b32_e32 v93, 0xffff0000, v72
	v_exp_f32_e32 v0, v0
	v_mul_f32_e32 v67, 0xbfb8aa3b, v93
	v_pk_mul_f32 v[76:77], v[94:95], v[76:77]
	v_pk_mul_f32 v[74:75], v[96:97], v[74:75]
	v_pk_mul_f32 v[90:91], v[98:99], v[90:91]
	v_exp_f32_e32 v67, v67
	v_pk_mul_f32 v[78:79], v[100:101], v[78:79]
	v_pk_mul_f32 v[76:77], v[82:83], v[76:77]
	v_pk_mul_f32 v[74:75], v[84:85], v[74:75]
	v_pk_mul_f32 v[82:83], v[86:87], v[90:91]
	v_pk_mul_f32 v[78:79], v[88:89], v[78:79]
	v_cvt_pk_bf16_f32 v76, v76, v77
	v_cvt_pk_bf16_f32 v77, v74, v75
	v_cvt_pk_bf16_f32 v74, v82, v83
	v_cvt_pk_bf16_f32 v75, v78, v79
	v_mov_b32_e32 v106, v76
	v_mov_b32_e32 v107, v77
	v_readfirstlane_b32 s98, v50
	v_readfirstlane_b32 s99, v51
	v_mov_b32_e32 v104, v74
	v_mov_b32_e32 v105, v75
	s_nop 1
	v_permlane32_swap_b32_e32 v104, v106
	v_permlane32_swap_b32_e32 v105, v107
	ds_write_b128 v118, v[104:107]
	v_add_f32_e32 v0, 1.0, v0
	v_lshlrev_b32_e32 v74, 16, v73
	v_rcp_f32_e32 v72, v0
	v_pk_mul_f32 v[58:59], v[58:59], v[66:67] op_sel_hi:[1,0]
	v_add_f32_e32 v0, 1.0, v67
	v_and_b32_e32 v75, 0xffff0000, v73
	v_mul_f32_e32 v67, 0xbfb8aa3b, v74
	v_exp_f32_e32 v67, v67
	v_mul_f32_e32 v73, 0xbfb8aa3b, v75
	v_exp_f32_e32 v77, v73
	v_rcp_f32_e32 v73, v0
	v_add_f32_e32 v0, 1.0, v67
	v_rcp_f32_e32 v76, v0
	v_add_f32_e32 v0, 1.0, v77
	v_rcp_f32_e32 v77, v0
	v_pk_mul_f32 v[72:73], v[72:73], v[92:93]
	v_pk_mul_f32 v[60:61], v[60:61], v[66:67] op_sel_hi:[1,0]
	v_pk_mul_f32 v[58:59], v[58:59], v[72:73]
	v_pk_mul_f32 v[72:73], v[76:77], v[74:75]
	v_cvt_pk_bf16_f32 v58, v58, v59
	v_pk_mul_f32 v[60:61], v[60:61], v[72:73]
	s_waitcnt vmcnt(2)
	v_lshlrev_b32_e32 v72, 16, v81
	v_cvt_pk_bf16_f32 v59, v60, v61
	v_mov_b32_e32 v106, v58
	v_mov_b32_e32 v107, v59
	v_lshlrev_b32_e32 v58, 16, v80
	v_mul_f32_e32 v0, 0xbfb8aa3b, v58
	v_and_b32_e32 v59, 0xffff0000, v80
	v_exp_f32_e32 v0, v0
	v_mul_f32_e32 v60, 0xbfb8aa3b, v59
	v_exp_f32_e32 v61, v60
	v_and_b32_e32 v73, 0xffff0000, v81
	v_add_f32_e32 v0, 1.0, v0
	v_rcp_f32_e32 v60, v0
	v_add_f32_e32 v0, 1.0, v61
	v_mul_f32_e32 v61, 0xbfb8aa3b, v72
	v_pk_mul_f32 v[62:63], v[62:63], v[66:67] op_sel_hi:[1,0]
	v_exp_f32_e32 v67, v61
	v_mul_f32_e32 v61, 0xbfb8aa3b, v73
	v_exp_f32_e32 v75, v61
	v_rcp_f32_e32 v61, v0
	v_add_f32_e32 v0, 1.0, v67
	v_rcp_f32_e32 v74, v0
	v_add_f32_e32 v0, 1.0, v75
	v_rcp_f32_e32 v75, v0
	v_pk_mul_f32 v[58:59], v[60:61], v[58:59]
	v_pk_mul_f32 v[60:61], v[64:65], v[66:67] op_sel_hi:[1,0]
	v_pk_mul_f32 v[58:59], v[62:63], v[58:59]
	v_pk_mul_f32 v[62:63], v[74:75], v[72:73]
	v_cvt_pk_bf16_f32 v58, v58, v59
	v_pk_mul_f32 v[60:61], v[60:61], v[62:63]
	s_waitcnt vmcnt(1)
	v_permlane32_swap_b32_e32 v178, v180
	v_permlane32_swap_b32_e32 v179, v181
	v_mov_b32_e32 v56, v178
	v_mov_b32_e32 v57, v179
	v_mov_b32_e32 v70, v180
	v_mov_b32_e32 v71, v181
	v_lshlrev_b32_e32 v62, 16, v71
	v_cvt_pk_bf16_f32 v59, v60, v61
	v_mov_b32_e32 v104, v58
	v_mov_b32_e32 v105, v59
	s_nop 1
	v_permlane32_swap_b32_e32 v104, v106
	v_permlane32_swap_b32_e32 v105, v107
	ds_write_b128 v119, v[104:107]
	v_lshlrev_b32_e32 v58, 16, v70
	v_mul_f32_e32 v0, 0xbfb8aa3b, v58
	v_and_b32_e32 v59, 0xffff0000, v70
	v_exp_f32_e32 v0, v0
	v_mul_f32_e32 v60, 0xbfb8aa3b, v59
	v_exp_f32_e32 v61, v60
	v_and_b32_e32 v63, 0xffff0000, v71
	v_add_f32_e32 v0, 1.0, v0
	v_rcp_f32_e32 v60, v0
	v_add_f32_e32 v0, 1.0, v61
	v_mul_f32_e32 v61, 0xbfb8aa3b, v62
	v_exp_f32_e32 v64, v61
	v_mul_f32_e32 v61, 0xbfb8aa3b, v63
	v_exp_f32_e32 v65, v61
	v_rcp_f32_e32 v61, v0
	v_add_f32_e32 v0, 1.0, v64
	v_rcp_f32_e32 v64, v0
	v_add_f32_e32 v0, 1.0, v65
	v_rcp_f32_e32 v65, v0
	v_pk_mul_f32 v[34:35], v[34:35], v[66:67] op_sel_hi:[1,0]
	v_pk_mul_f32 v[58:59], v[60:61], v[58:59]
	v_pk_mul_f32 v[36:37], v[36:37], v[66:67] op_sel_hi:[1,0]
	v_pk_mul_f32 v[34:35], v[34:35], v[58:59]
	v_pk_mul_f32 v[58:59], v[64:65], v[62:63]
	v_cvt_pk_bf16_f32 v34, v34, v35
	v_pk_mul_f32 v[36:37], v[36:37], v[58:59]
	v_pk_mul_f32 v[38:39], v[38:39], v[66:67] op_sel_hi:[1,0]
	v_cvt_pk_bf16_f32 v35, v36, v37
	v_mov_b32_e32 v106, v34
	v_mov_b32_e32 v107, v35
	s_waitcnt vmcnt(1)
	v_lshlrev_b32_e32 v34, 16, v56
	v_mul_f32_e32 v0, 0xbfb8aa3b, v34
	v_and_b32_e32 v35, 0xffff0000, v56
	v_exp_f32_e32 v0, v0
	v_mul_f32_e32 v36, 0xbfb8aa3b, v35
	v_exp_f32_e32 v37, v36
	v_lshlrev_b32_e32 v56, 16, v57
	v_add_f32_e32 v0, 1.0, v0
	v_rcp_f32_e32 v36, v0
	v_add_f32_e32 v0, 1.0, v37
	v_and_b32_e32 v57, 0xffff0000, v57
	v_mul_f32_e32 v37, 0xbfb8aa3b, v56
	v_exp_f32_e32 v58, v37
	v_mul_f32_e32 v37, 0xbfb8aa3b, v57
	v_exp_f32_e32 v59, v37
	v_rcp_f32_e32 v37, v0
	v_add_f32_e32 v0, 1.0, v58
	v_rcp_f32_e32 v58, v0
	v_add_f32_e32 v0, 1.0, v59
	v_rcp_f32_e32 v59, v0
	v_pk_mul_f32 v[34:35], v[36:37], v[34:35]
	v_pk_mul_f32 v[36:37], v[40:41], v[66:67] op_sel_hi:[1,0]
	v_pk_mul_f32 v[34:35], v[38:39], v[34:35]
	v_pk_mul_f32 v[38:39], v[58:59], v[56:57]
	v_add_co_u32_e32 v60, vcc, s0, v68
	v_pk_mul_f32 v[36:37], v[36:37], v[38:39]
	s_waitcnt vmcnt(0)
	v_permlane32_swap_b32_e32 v182, v184
	v_permlane32_swap_b32_e32 v183, v185
	v_mov_b32_e32 v52, v182
	v_mov_b32_e32 v53, v183
	v_mov_b32_e32 v54, v184
	v_mov_b32_e32 v55, v185
	v_lshlrev_b32_e32 v38, 16, v54
	v_and_b32_e32 v39, 0xffff0000, v54
	v_mul_f32_e32 v0, 0xbfb8aa3b, v38
	v_exp_f32_e32 v0, v0
	v_mul_f32_e32 v40, 0xbfb8aa3b, v39
	v_exp_f32_e32 v41, v40
	v_addc_co_u32_e32 v61, vcc, 0, v69, vcc
	v_add_f32_e32 v0, 1.0, v0
	v_rcp_f32_e32 v40, v0
	v_add_f32_e32 v0, 1.0, v41
	v_rcp_f32_e32 v41, v0
	v_cvt_pk_bf16_f32 v34, v34, v35
	v_cvt_pk_bf16_f32 v35, v36, v37
	v_mov_b32_e32 v104, v34
	v_mov_b32_e32 v105, v35
	s_nop 1
	v_permlane32_swap_b32_e32 v104, v106
	v_permlane32_swap_b32_e32 v105, v107
	ds_write_b128 v120, v[104:107]
	v_pk_mul_f32 v[36:37], v[40:41], v[38:39]
	v_lshlrev_b32_e32 v38, 16, v55
	v_and_b32_e32 v39, 0xffff0000, v55
	v_mul_f32_e32 v0, 0xbfb8aa3b, v38
	v_exp_f32_e32 v0, v0
	v_mul_f32_e32 v40, 0xbfb8aa3b, v39
	v_exp_f32_e32 v40, v40
	v_pk_mul_f32 v[34:35], v[42:43], v[66:67] op_sel_hi:[1,0]
	v_add_f32_e32 v0, 1.0, v0
	v_pk_mul_f32 v[34:35], v[34:35], v[36:37]
	v_rcp_f32_e32 v36, v0
	v_add_f32_e32 v0, 1.0, v40
	v_rcp_f32_e32 v37, v0
	s_mov_b64 s[0:1], 0x4429e00
	v_lshl_add_u64 v[42:43], v[68:69], 0, s[0:1]
	v_pk_mul_f32 v[40:41], v[44:45], v[66:67] op_sel_hi:[1,0]
	v_lshl_add_u64 v[116:117], v[42:43], 0, v[108:109]
	global_load_dwordx4 v[186:189], v[116:117], off
	v_pk_mul_f32 v[36:37], v[36:37], v[38:39]
	v_cvt_pk_bf16_f32 v34, v34, v35
	v_pk_mul_f32 v[36:37], v[40:41], v[36:37]
	s_waitcnt vmcnt(1)
	v_lshlrev_b32_e32 v40, 16, v53
	v_cvt_pk_bf16_f32 v35, v36, v37
	v_mov_b32_e32 v106, v34
	v_mov_b32_e32 v107, v35
	v_lshlrev_b32_e32 v34, 16, v52
	v_mul_f32_e32 v0, 0xbfb8aa3b, v34
	v_and_b32_e32 v35, 0xffff0000, v52
	v_exp_f32_e32 v0, v0
	v_mul_f32_e32 v36, 0xbfb8aa3b, v35
	v_exp_f32_e32 v37, v36
	v_and_b32_e32 v41, 0xffff0000, v53
	v_add_f32_e32 v0, 1.0, v0
	v_rcp_f32_e32 v36, v0
	v_add_f32_e32 v0, 1.0, v37
	v_rcp_f32_e32 v37, v0
	v_mul_f32_e32 v0, 0xbfb8aa3b, v40
	v_pk_mul_f32 v[38:39], v[46:47], v[66:67] op_sel_hi:[1,0]
	v_exp_f32_e32 v0, v0
	v_mul_f32_e32 v46, 0xbfb8aa3b, v41
	v_exp_f32_e32 v46, v46
	v_pk_mul_f32 v[34:35], v[36:37], v[34:35]
	v_add_f32_e32 v0, 1.0, v0
	v_rcp_f32_e32 v36, v0
	v_add_f32_e32 v0, 1.0, v46
	v_rcp_f32_e32 v37, v0
	v_pk_mul_f32 v[34:35], v[38:39], v[34:35]
	v_pk_mul_f32 v[38:39], v[48:49], v[66:67] op_sel_hi:[1,0]
	v_cvt_pk_bf16_f32 v34, v34, v35
	v_pk_mul_f32 v[36:37], v[36:37], v[40:41]
	v_mov_b32_e32 v0, v250
	v_pk_mul_f32 v[36:37], v[38:39], v[36:37]
	s_nop 0
	v_permlane32_swap_b32_e32 v250, v0
	v_cvt_pk_bf16_f32 v35, v36, v37
	v_mov_b32_e32 v104, v34
	v_mov_b32_e32 v105, v35
	s_nop 1
	v_permlane32_swap_b32_e32 v104, v106
	v_permlane32_swap_b32_e32 v105, v107
	ds_write_b128 v121, v[104:107]
	ds_read_b128 v[124:127], v122
	ds_read_b128 v[128:131], v122 offset:1024
	ds_read_b128 v[132:135], v122 offset:2048
	ds_read_b128 v[136:139], v122 offset:3072
	s_waitcnt lgkmcnt(3)
	global_store_dwordx4 v144, v[124:127], s[98:99] sc0 sc1
	s_waitcnt lgkmcnt(2)
	global_store_dwordx4 v145, v[128:131], s[98:99] sc0 sc1
	s_waitcnt lgkmcnt(1)
	global_store_dwordx4 v146, v[132:135], s[98:99] sc0 sc1
	s_waitcnt lgkmcnt(0)
	global_store_dwordx4 v147, v[136:139], s[98:99] sc0 sc1
	global_load_dwordx4 v[190:193], v[116:117], off offset:32
	global_load_dwordx4 v[194:197], v[116:117], off offset:64
	s_nop 0
	global_load_dwordx4 v[198:201], v[116:117], off offset:96
	v_add_f32_e32 v0, v250, v0
	v_rcp_f32_e32 v0, v0
	s_mov_b64 s[0:1], 0x11000
	v_pk_mul_f32 v[18:19], v[18:19], v[0:1] op_sel_hi:[1,0]
	v_pk_mul_f32 v[20:21], v[20:21], v[0:1] op_sel_hi:[1,0]
	v_pk_mul_f32 v[22:23], v[22:23], v[0:1] op_sel_hi:[1,0]
	v_pk_mul_f32 v[2:3], v[2:3], v[0:1] op_sel_hi:[1,0]
	v_pk_mul_f32 v[4:5], v[4:5], v[0:1] op_sel_hi:[1,0]
	v_pk_mul_f32 v[6:7], v[6:7], v[0:1] op_sel_hi:[1,0]
	s_waitcnt vmcnt(7)
	v_permlane32_swap_b32_e32 v186, v188
	v_permlane32_swap_b32_e32 v187, v189
	v_mov_b32_e32 v44, v186
	v_mov_b32_e32 v45, v187
	v_mov_b32_e32 v60, v188
	v_mov_b32_e32 v61, v189
	v_lshlrev_b32_e32 v42, 16, v60
	v_mul_f32_e32 v43, 0xbfb8aa3b, v42
	v_exp_f32_e32 v52, v43
	v_and_b32_e32 v43, 0xffff0000, v60
	v_mul_f32_e32 v53, 0xbfb8aa3b, v43
	v_lshlrev_b32_e32 v54, 16, v61
	v_and_b32_e32 v55, 0xffff0000, v61
	v_exp_f32_e32 v53, v53
	v_mul_f32_e32 v56, 0xbfb8aa3b, v54
	v_mul_f32_e32 v57, 0xbfb8aa3b, v55
	v_exp_f32_e32 v56, v56
	v_exp_f32_e32 v57, v57
	v_add_f32_e32 v52, 1.0, v52
	v_add_f32_e32 v53, 1.0, v53
	v_rcp_f32_e32 v52, v52
	v_rcp_f32_e32 v53, v53
	v_add_f32_e32 v56, 1.0, v56
	v_add_f32_e32 v57, 1.0, v57
	v_rcp_f32_e32 v56, v56
	v_rcp_f32_e32 v57, v57
	v_pk_mul_f32 v[42:43], v[52:53], v[42:43]
	s_nop 0
	v_pk_mul_f32 v[18:19], v[18:19], v[42:43]
	v_pk_mul_f32 v[42:43], v[56:57], v[54:55]
	s_nop 0
	v_pk_mul_f32 v[20:21], v[20:21], v[42:43]
	v_cvt_pk_bf16_f32 v42, v18, v19
	v_lshl_add_u64 v[18:19], v[50:51], 0, s[0:1]
	s_mov_b32 s0, 0x11000
	v_cvt_pk_bf16_f32 v43, v20, v21
	v_add_co_u32_e32 v20, vcc, s0, v50
	s_nop 1
	v_addc_co_u32_e32 v21, vcc, 0, v51, vcc
	v_mov_b32_e32 v106, v42
	v_mov_b32_e32 v107, v43
	s_waitcnt vmcnt(7)
	v_lshlrev_b32_e32 v20, 16, v44
	v_mul_f32_e32 v21, 0xbfb8aa3b, v20
	v_exp_f32_e32 v42, v21
	v_and_b32_e32 v21, 0xffff0000, v44
	v_mul_f32_e32 v43, 0xbfb8aa3b, v21
	v_lshlrev_b32_e32 v44, 16, v45
	v_and_b32_e32 v45, 0xffff0000, v45
	v_exp_f32_e32 v43, v43
	v_mul_f32_e32 v50, 0xbfb8aa3b, v44
	v_mul_f32_e32 v51, 0xbfb8aa3b, v45
	v_exp_f32_e32 v50, v50
	v_exp_f32_e32 v51, v51
	v_add_f32_e32 v42, 1.0, v42
	v_add_f32_e32 v43, 1.0, v43
	v_rcp_f32_e32 v42, v42
	v_rcp_f32_e32 v43, v43
	v_add_f32_e32 v50, 1.0, v50
	v_add_f32_e32 v51, 1.0, v51
	v_rcp_f32_e32 v50, v50
	v_rcp_f32_e32 v51, v51
	v_pk_mul_f32 v[20:21], v[42:43], v[20:21]
	s_nop 0
	v_pk_mul_f32 v[20:21], v[22:23], v[20:21]
	v_pk_mul_f32 v[22:23], v[24:25], v[0:1] op_sel_hi:[1,0]
	v_pk_mul_f32 v[24:25], v[50:51], v[44:45]
	v_cvt_pk_bf16_f32 v20, v20, v21
	v_pk_mul_f32 v[22:23], v[22:23], v[24:25]
	v_pk_mul_f32 v[24:25], v[26:27], v[0:1] op_sel_hi:[1,0]
	v_cvt_pk_bf16_f32 v21, v22, v23
	v_readfirstlane_b32 s98, v18
	v_readfirstlane_b32 s99, v19
	v_mov_b32_e32 v104, v20
	v_mov_b32_e32 v105, v21
	s_nop 1
	v_permlane32_swap_b32_e32 v104, v106
	v_permlane32_swap_b32_e32 v105, v107
	ds_write_b128 v118, v[104:107]
	s_waitcnt vmcnt(2)
	v_permlane32_swap_b32_e32 v190, v192
	v_permlane32_swap_b32_e32 v191, v193
	v_mov_b32_e32 v40, v190
	v_mov_b32_e32 v41, v191
	v_mov_b32_e32 v46, v192
	v_mov_b32_e32 v47, v193
	v_lshlrev_b32_e32 v20, 16, v46
	v_mul_f32_e32 v21, 0xbfb8aa3b, v20
	v_exp_f32_e32 v22, v21
	v_and_b32_e32 v21, 0xffff0000, v46
	v_mul_f32_e32 v23, 0xbfb8aa3b, v21
	v_lshlrev_b32_e32 v26, 16, v47
	v_and_b32_e32 v27, 0xffff0000, v47
	v_exp_f32_e32 v23, v23
	v_mul_f32_e32 v42, 0xbfb8aa3b, v26
	v_mul_f32_e32 v43, 0xbfb8aa3b, v27
	v_exp_f32_e32 v42, v42
	v_exp_f32_e32 v43, v43
	v_add_f32_e32 v22, 1.0, v22
	v_add_f32_e32 v23, 1.0, v23
	v_rcp_f32_e32 v22, v22
	v_rcp_f32_e32 v23, v23
	v_add_f32_e32 v42, 1.0, v42
	v_add_f32_e32 v43, 1.0, v43
	v_rcp_f32_e32 v42, v42
	v_rcp_f32_e32 v43, v43
	v_pk_mul_f32 v[20:21], v[22:23], v[20:21]
	v_pk_mul_f32 v[22:23], v[28:29], v[0:1] op_sel_hi:[1,0]
	v_pk_mul_f32 v[20:21], v[24:25], v[20:21]
	v_pk_mul_f32 v[24:25], v[42:43], v[26:27]
	v_cvt_pk_bf16_f32 v20, v20, v21
	v_pk_mul_f32 v[22:23], v[22:23], v[24:25]
	s_waitcnt vmcnt(2)
	v_lshlrev_b32_e32 v26, 16, v41
	v_cvt_pk_bf16_f32 v21, v22, v23
	v_mov_b32_e32 v106, v20
	v_mov_b32_e32 v107, v21
	v_lshlrev_b32_e32 v20, 16, v40
	v_mul_f32_e32 v21, 0xbfb8aa3b, v20
	v_exp_f32_e32 v22, v21
	v_and_b32_e32 v21, 0xffff0000, v40
	v_mul_f32_e32 v23, 0xbfb8aa3b, v21
	v_and_b32_e32 v27, 0xffff0000, v41
	v_exp_f32_e32 v23, v23
	v_mul_f32_e32 v28, 0xbfb8aa3b, v26
	v_mul_f32_e32 v29, 0xbfb8aa3b, v27
	v_exp_f32_e32 v28, v28
	v_exp_f32_e32 v29, v29
	v_add_f32_e32 v22, 1.0, v22
	v_add_f32_e32 v23, 1.0, v23
	v_rcp_f32_e32 v22, v22
	v_rcp_f32_e32 v23, v23
	v_add_f32_e32 v28, 1.0, v28
	v_add_f32_e32 v29, 1.0, v29
	v_rcp_f32_e32 v28, v28
	v_rcp_f32_e32 v29, v29
	v_pk_mul_f32 v[24:25], v[30:31], v[0:1] op_sel_hi:[1,0]
	v_pk_mul_f32 v[20:21], v[22:23], v[20:21]
	v_pk_mul_f32 v[22:23], v[32:33], v[0:1] op_sel_hi:[1,0]
	v_pk_mul_f32 v[20:21], v[24:25], v[20:21]
	v_pk_mul_f32 v[24:25], v[28:29], v[26:27]
	v_cvt_pk_bf16_f32 v20, v20, v21
	v_pk_mul_f32 v[22:23], v[22:23], v[24:25]
	s_waitcnt vmcnt(1)
	v_permlane32_swap_b32_e32 v194, v196
	v_permlane32_swap_b32_e32 v195, v197
	v_mov_b32_e32 v38, v194
	v_mov_b32_e32 v39, v195
	v_mov_b32_e32 v48, v196
	v_mov_b32_e32 v49, v197
	v_lshlrev_b32_e32 v24, 16, v49
	v_cvt_pk_bf16_f32 v21, v22, v23
	v_mov_b32_e32 v104, v20
	v_mov_b32_e32 v105, v21
	s_nop 1
	v_permlane32_swap_b32_e32 v104, v106
	v_permlane32_swap_b32_e32 v105, v107
	ds_write_b128 v119, v[104:107]
	v_lshlrev_b32_e32 v20, 16, v48
	v_mul_f32_e32 v21, 0xbfb8aa3b, v20
	v_exp_f32_e32 v22, v21
	v_and_b32_e32 v21, 0xffff0000, v48
	v_mul_f32_e32 v23, 0xbfb8aa3b, v21
	v_and_b32_e32 v25, 0xffff0000, v49
	v_exp_f32_e32 v23, v23
	v_mul_f32_e32 v26, 0xbfb8aa3b, v24
	v_mul_f32_e32 v27, 0xbfb8aa3b, v25
	v_exp_f32_e32 v26, v26
	v_exp_f32_e32 v27, v27
	v_add_f32_e32 v22, 1.0, v22
	v_add_f32_e32 v23, 1.0, v23
	v_rcp_f32_e32 v22, v22
	v_rcp_f32_e32 v23, v23
	v_add_f32_e32 v26, 1.0, v26
	v_add_f32_e32 v27, 1.0, v27
	v_rcp_f32_e32 v26, v26
	v_rcp_f32_e32 v27, v27
	v_pk_mul_f32 v[20:21], v[22:23], v[20:21]
	s_nop 0
	v_pk_mul_f32 v[2:3], v[2:3], v[20:21]
	v_pk_mul_f32 v[20:21], v[26:27], v[24:25]
	v_cvt_pk_bf16_f32 v2, v2, v3
	v_pk_mul_f32 v[4:5], v[4:5], v[20:21]
	s_waitcnt vmcnt(1)
	v_lshlrev_b32_e32 v20, 16, v39
	v_cvt_pk_bf16_f32 v3, v4, v5
	v_mov_b32_e32 v106, v2
	v_mov_b32_e32 v107, v3
	v_lshlrev_b32_e32 v2, 16, v38
	v_mul_f32_e32 v3, 0xbfb8aa3b, v2
	v_exp_f32_e32 v4, v3
	v_and_b32_e32 v3, 0xffff0000, v38
	v_mul_f32_e32 v5, 0xbfb8aa3b, v3
	v_and_b32_e32 v21, 0xffff0000, v39
	v_exp_f32_e32 v5, v5
	v_mul_f32_e32 v22, 0xbfb8aa3b, v20
	v_mul_f32_e32 v23, 0xbfb8aa3b, v21
	v_exp_f32_e32 v22, v22
	v_exp_f32_e32 v23, v23
	v_add_f32_e32 v4, 1.0, v4
	v_add_f32_e32 v5, 1.0, v5
	v_rcp_f32_e32 v4, v4
	v_rcp_f32_e32 v5, v5
	v_add_f32_e32 v22, 1.0, v22
	v_add_f32_e32 v23, 1.0, v23
	v_rcp_f32_e32 v22, v22
	v_rcp_f32_e32 v23, v23
	v_pk_mul_f32 v[2:3], v[4:5], v[2:3]
	v_pk_mul_f32 v[4:5], v[8:9], v[0:1] op_sel_hi:[1,0]
	v_pk_mul_f32 v[2:3], v[6:7], v[2:3]
	v_pk_mul_f32 v[6:7], v[22:23], v[20:21]
	v_cvt_pk_bf16_f32 v2, v2, v3
	v_pk_mul_f32 v[4:5], v[4:5], v[6:7]
	s_waitcnt vmcnt(0)
	v_permlane32_swap_b32_e32 v198, v200
	v_permlane32_swap_b32_e32 v199, v201
	v_mov_b32_e32 v34, v198
	v_mov_b32_e32 v35, v199
	v_mov_b32_e32 v36, v200
	v_mov_b32_e32 v37, v201
	v_lshlrev_b32_e32 v8, 16, v37
	v_cvt_pk_bf16_f32 v3, v4, v5
	v_mov_b32_e32 v104, v2
	v_mov_b32_e32 v105, v3
	s_nop 1
	v_permlane32_swap_b32_e32 v104, v106
	v_permlane32_swap_b32_e32 v105, v107
	ds_write_b128 v120, v[104:107]
	v_lshlrev_b32_e32 v2, 16, v36
	v_mul_f32_e32 v3, 0xbfb8aa3b, v2
	v_exp_f32_e32 v4, v3
	v_and_b32_e32 v3, 0xffff0000, v36
	v_mul_f32_e32 v5, 0xbfb8aa3b, v3
	v_and_b32_e32 v9, 0xffff0000, v37
	v_exp_f32_e32 v5, v5
	v_pk_mul_f32 v[6:7], v[10:11], v[0:1] op_sel_hi:[1,0]
	v_mul_f32_e32 v10, 0xbfb8aa3b, v8
	v_mul_f32_e32 v11, 0xbfb8aa3b, v9
	v_exp_f32_e32 v10, v10
	v_exp_f32_e32 v11, v11
	v_add_f32_e32 v4, 1.0, v4
	v_add_f32_e32 v5, 1.0, v5
	v_rcp_f32_e32 v4, v4
	v_rcp_f32_e32 v5, v5
	v_add_f32_e32 v10, 1.0, v10
	v_add_f32_e32 v11, 1.0, v11
	v_rcp_f32_e32 v10, v10
	v_rcp_f32_e32 v11, v11
	v_pk_mul_f32 v[2:3], v[4:5], v[2:3]
	v_pk_mul_f32 v[4:5], v[12:13], v[0:1] op_sel_hi:[1,0]
	v_pk_mul_f32 v[2:3], v[6:7], v[2:3]
	v_pk_mul_f32 v[6:7], v[10:11], v[8:9]
	v_cvt_pk_bf16_f32 v2, v2, v3
	v_pk_mul_f32 v[4:5], v[4:5], v[6:7]
	s_waitcnt vmcnt(0)
	v_lshlrev_b32_e32 v8, 16, v35
	v_cvt_pk_bf16_f32 v3, v4, v5
	v_mov_b32_e32 v106, v2
	v_mov_b32_e32 v107, v3
	v_lshlrev_b32_e32 v2, 16, v34
	v_mul_f32_e32 v3, 0xbfb8aa3b, v2
	v_exp_f32_e32 v4, v3
	v_and_b32_e32 v3, 0xffff0000, v34
	v_mul_f32_e32 v5, 0xbfb8aa3b, v3
	v_and_b32_e32 v9, 0xffff0000, v35
	v_exp_f32_e32 v5, v5
	v_mul_f32_e32 v10, 0xbfb8aa3b, v8
	v_mul_f32_e32 v11, 0xbfb8aa3b, v9
	v_exp_f32_e32 v10, v10
	v_exp_f32_e32 v11, v11
	v_add_f32_e32 v4, 1.0, v4
	v_add_f32_e32 v5, 1.0, v5
	v_rcp_f32_e32 v4, v4
	v_rcp_f32_e32 v5, v5
	v_add_f32_e32 v10, 1.0, v10
	v_add_f32_e32 v11, 1.0, v11
	v_rcp_f32_e32 v10, v10
	v_rcp_f32_e32 v11, v11
	v_pk_mul_f32 v[6:7], v[14:15], v[0:1] op_sel_hi:[1,0]
	v_pk_mul_f32 v[2:3], v[4:5], v[2:3]
	v_pk_mul_f32 v[4:5], v[16:17], v[0:1] op_sel_hi:[1,0]
	v_pk_mul_f32 v[2:3], v[6:7], v[2:3]
	v_pk_mul_f32 v[6:7], v[10:11], v[8:9]
	v_cvt_pk_bf16_f32 v2, v2, v3
	v_pk_mul_f32 v[4:5], v[4:5], v[6:7]
	s_nop 0
	v_cvt_pk_bf16_f32 v3, v4, v5
	v_mov_b32_e32 v104, v2
	v_mov_b32_e32 v105, v3
	s_nop 1
	v_permlane32_swap_b32_e32 v104, v106
	v_permlane32_swap_b32_e32 v105, v107
	ds_write_b128 v121, v[104:107]
	ds_read_b128 v[124:127], v122
	ds_read_b128 v[128:131], v122 offset:1024
	ds_read_b128 v[132:135], v122 offset:2048
	ds_read_b128 v[136:139], v122 offset:3072
	s_waitcnt lgkmcnt(3)
	global_store_dwordx4 v144, v[124:127], s[98:99] sc0 sc1
	s_waitcnt lgkmcnt(2)
	global_store_dwordx4 v145, v[128:131], s[98:99] sc0 sc1
	s_waitcnt lgkmcnt(1)
	global_store_dwordx4 v146, v[132:135], s[98:99] sc0 sc1
	s_waitcnt lgkmcnt(0)
	global_store_dwordx4 v147, v[136:139], s[98:99] sc0 sc1
